# non-temporal loads on read-once f32 input streams (weight conversion, conditioning GEMV rows, x rows in phase 1) on top of XCD-local seams and pipelined GEMV
# speedup vs baseline: 1.0152x; 1.0056x over previous
; template <bool CTX>
; __device__ __forceinline__ void norm_rows(const float* X, int nrows, const float* g, const float* modsl, int cshift, int cscale, bf16* H, bf16* XC, int gw, int NGW, int lane) {
;     const int rpw = (nrows + NGW - 1) / NGW; int row = gw * rpw; const int rend = (row + rpw < nrows) ? row + rpw : nrows; if (row >= rend) return;
;     f32x4 v[8], nv[8], gm[8], sh[8]; int cur = -1;
; #pragma unroll
;     for (int j = 0; j < 8; ++j) { nv[j] = (f32x4){0.f, 0.f, 0.f, 0.f}; gm[j] = nv[j]; sh[j] = nv[j]; }
;     { const f32x4* xr = (const f32x4*)(X + (size_t)row * D) + lane;
; #pragma unroll
;       for (int j = 0; j < 8; ++j) v[j] = xr[64 * j]; }
.LBB0_340:
	s_andn2_b64 vcc, exec, s[6:7]
	s_cbranch_vccnz .LBB0_363
	s_cmp_eq_u32 s48, 1
	s_cbranch_scc0 .LBB0_363
	s_load_dwordx2 s[6:7], s[0:1], 0x30
	v_readlane_b32 s2, v254, 30
	s_mul_i32 s10, s2, s38
	s_add_i32 s2, s10, s2
	s_min_i32 s2, s2, 0x4000
	s_cmp_ge_i32 s10, s2
	s_waitcnt vmcnt(0)
	v_lshlrev_b32_e32 v132, 4, v164
	v_lshlrev_b32_e32 v134, 3, v164
	s_cbranch_scc1 .LBB0_351
	s_load_dwordx2 s[8:9], s[0:1], 0x0
	s_waitcnt lgkmcnt(0)
	s_add_u32 s5, s82, 0x100000
	s_addc_u32 s12, s83, 0
	s_ashr_i32 s11, s10, 31
	s_lshl_b64 s[14:15], s[10:11], 13
	s_add_u32 s8, s8, s14
	s_addc_u32 s9, s9, s15
	v_mov_b32_e32 v133, v0
	v_lshl_add_u64 v[2:3], s[8:9], 0, v[132:133]
	v_add_co_u32_e32 v32, vcc, s41, v2
	global_load_dwordx4 v[28:31], v132, s[8:9] nt
	global_load_dwordx4 v[24:27], v132, s[8:9] offset:1024 nt
	global_load_dwordx4 v[20:23], v132, s[8:9] offset:2048 nt
	global_load_dwordx4 v[16:19], v132, s[8:9] offset:3072 nt
	v_addc_co_u32_e32 v33, vcc, 0, v3, vcc
	global_load_dwordx4 v[12:15], v[32:33], off nt
	global_load_dwordx4 v[8:11], v[32:33], off offset:1024 nt
	global_load_dwordx4 v[4:7], v[32:33], off offset:2048 nt
	global_load_dwordx4 v[72:75], v[32:33], off offset:3072 nt
	v_cmp_lt_i32_e32 vcc, v215, v225
	v_lshl_add_u64 v[136:137], s[6:7], 0, v[132:133]
	s_mov_b64 s[8:9], 0x1400
	v_cndmask_b32_e32 v1, v217, v215, vcc
	v_lshlrev_b32_e32 v152, 2, v1
	v_xor_b32_e32 v1, 2, v217
	v_cmp_lt_i32_e32 vcc, v1, v225
	v_lshl_add_u64 v[140:141], v[136:137], 0, s[8:9]
	s_mov_b64 s[8:9], 0x1800
	v_cndmask_b32_e32 v1, v217, v1, vcc
	v_lshlrev_b32_e32 v153, 2, v1
	v_xor_b32_e32 v1, 4, v217
	v_cmp_lt_i32_e32 vcc, v1, v225
	v_lshl_add_u64 v[142:143], v[136:137], 0, s[8:9]
	s_mov_b64 s[8:9], 0x1c00
	v_cndmask_b32_e32 v1, v217, v1, vcc
	v_lshlrev_b32_e32 v154, 2, v1
	v_xor_b32_e32 v1, 8, v217
	v_cmp_lt_i32_e32 vcc, v1, v225
	v_lshl_add_u64 v[144:145], v[136:137], 0, s[8:9]
	s_lshl_b64 s[8:9], s[10:11], 12
	v_cndmask_b32_e32 v1, v217, v1, vcc
	v_cmp_lt_i32_e32 vcc, v222, v225
	s_add_u32 s8, s82, s8
	v_lshlrev_b32_e32 v155, 2, v1
	v_cndmask_b32_e32 v1, v217, v222, vcc
	v_cmp_lt_i32_e32 vcc, v223, v225
	v_mov_b32_e32 v135, v0
	s_addc_u32 s9, s83, s9
	v_lshlrev_b32_e32 v156, 2, v1
	v_cndmask_b32_e32 v1, v217, v223, vcc
	v_lshl_add_u64 v[32:33], s[8:9], 0, v[134:135]
	s_mov_b64 s[8:9], 0xc000000
	v_lshl_add_u64 v[148:149], v[2:3], 0, s[44:45]
	v_mov_b32_e32 v2, v0
	v_mov_b32_e32 v3, v0
	v_lshlrev_b32_e32 v157, 2, v1
	v_lshl_add_u64 v[146:147], v[32:33], 0, s[8:9]
	v_mov_b32_e32 v1, v0
	v_mov_b64_e32 v[50:51], v[2:3]
	v_mov_b64_e32 v[54:55], v[2:3]
	v_mov_b64_e32 v[58:59], v[2:3]
	v_mov_b64_e32 v[62:63], v[2:3]
	v_mov_b64_e32 v[34:35], v[2:3]
	v_mov_b64_e32 v[38:39], v[2:3]
	v_mov_b64_e32 v[42:43], v[2:3]
	v_mov_b64_e32 v[46:47], v[2:3]
	v_mov_b64_e32 v[126:127], v[2:3]
	v_mov_b64_e32 v[118:119], v[2:3]
	v_mov_b64_e32 v[110:111], v[2:3]
	v_mov_b64_e32 v[102:103], v[2:3]
	v_mov_b64_e32 v[90:91], v[2:3]
	v_mov_b64_e32 v[86:87], v[2:3]
	v_mov_b64_e32 v[78:79], v[2:3]
	v_mov_b64_e32 v[66:67], v[2:3]
	v_mov_b64_e32 v[130:131], v[2:3]
	v_mov_b64_e32 v[122:123], v[2:3]
	v_mov_b64_e32 v[114:115], v[2:3]
	v_mov_b64_e32 v[106:107], v[2:3]
	v_mov_b64_e32 v[98:99], v[2:3]
	v_mov_b64_e32 v[94:95], v[2:3]
	v_mov_b64_e32 v[82:83], v[2:3]
	v_mov_b64_e32 v[70:71], v[2:3]
	s_mov_b32 s14, -1
	v_lshl_add_u64 v[138:139], v[136:137], 0, s[96:97]
	v_lshlrev_b32_e32 v150, 4, v164
	v_mov_b64_e32 v[48:49], v[0:1]
	v_mov_b64_e32 v[52:53], v[0:1]
	v_mov_b64_e32 v[56:57], v[0:1]
	v_mov_b64_e32 v[60:61], v[0:1]
	v_mov_b64_e32 v[32:33], v[0:1]
	v_mov_b64_e32 v[36:37], v[0:1]
	v_mov_b64_e32 v[40:41], v[0:1]
	v_mov_b64_e32 v[44:45], v[0:1]
	v_mov_b64_e32 v[124:125], v[0:1]
	v_mov_b64_e32 v[116:117], v[0:1]
	v_mov_b64_e32 v[108:109], v[0:1]
	v_mov_b64_e32 v[100:101], v[0:1]
	v_mov_b64_e32 v[88:89], v[0:1]
	v_mov_b64_e32 v[84:85], v[0:1]
	v_mov_b64_e32 v[76:77], v[0:1]
	v_mov_b64_e32 v[64:65], v[0:1]
	v_mov_b64_e32 v[128:129], v[0:1]
	v_mov_b64_e32 v[120:121], v[0:1]
	v_mov_b64_e32 v[112:113], v[0:1]
	v_mov_b64_e32 v[104:105], v[0:1]
	v_mov_b64_e32 v[96:97], v[0:1]
	v_mov_b64_e32 v[92:93], v[0:1]
	v_mov_b64_e32 v[80:81], v[0:1]
	v_mov_b64_e32 v[68:69], v[0:1]
	s_waitcnt vmcnt(0)
	v_mov_b32_e32 v133, v72
	v_mov_b32_e32 v3, v73
	v_mov_b32_e32 v2, v74
	v_mov_b32_e32 v1, v75
	s_branch .LBB0_345

; template <bool CTX>
; __device__ __forceinline__ void norm_rows(const float* X, int nrows, const float* g, const float* modsl, int cshift, int cscale, bf16* H, bf16* XC, int gw, int NGW, int lane) {
;     ...
;         const int nrow = row + 1; const bool more = nrow < rend;
;         if (more) { const f32x4* xr = (const f32x4*)(X + (size_t)nrow * D) + lane;
; #pragma unroll
;             for (int j = 0; j < 8; ++j) nv[j] = xr[64 * j]; }
.LBB0_345:
	s_add_i32 s13, s10, 1
	s_cmp_lt_i32 s13, s2
	s_cselect_b64 s[8:9], -1, 0
	s_cmp_ge_i32 s13, s2
	s_cbranch_scc1 .LBB0_347
	v_add_co_u32_e32 v48, vcc, 0x1000, v148
	global_load_dwordx4 v[44:47], v[148:149], off nt
	global_load_dwordx4 v[40:43], v[148:149], off offset:1024 nt
	global_load_dwordx4 v[36:39], v[148:149], off offset:2048 nt
	global_load_dwordx4 v[32:35], v[148:149], off offset:3072 nt
	v_addc_co_u32_e32 v49, vcc, 0, v149, vcc
	global_load_dwordx4 v[60:63], v[48:49], off nt
	global_load_dwordx4 v[56:59], v[48:49], off offset:1024 nt
	global_load_dwordx4 v[52:55], v[48:49], off offset:2048 nt
	s_nop 0
	global_load_dwordx4 v[48:51], v[48:49], off offset:3072 nt

; __device__ __forceinline__ void ada_phase(LAS unsigned char* lds, const float* c, const float* c_ctx, const float* ada_w, const float* ada_b, float* mods, int G, int bid, int tid, int item0, int item1) {
;     ...
;         const int l = item / 384, n0 = (item % 384) * 32;
;         const float* wp = ada_w + (size_t)l * D * MODW + n0 + 4 * cgp;
;         f32x4 acc[9];
; #pragma unroll
;         for (int r = 0; r < 9; ++r) acc[r] = (f32x4){0.f, 0.f, 0.f, 0.f};
; #pragma unroll 16
;         for (int i = 0; i < 32; ++i) { const int k = ks + 64 * i; const f32x4 w = *(const f32x4*)(wp + (size_t)k * MODW);
; #pragma unroll
;             for (int r = 0; r < 9; ++r) acc[r] += w * sT[k * 9 + r]; }
.Lada_k:
	v_lshl_add_u64 v[26:27], v[8:9], 0, s[14:15]
	global_load_dwordx4 v[60:63], v[26:27], off nt
	s_add_u32 s14, s14, 0x300000
	s_addc_u32 s15, s15, 0
	v_lshl_add_u64 v[26:27], v[8:9], 0, s[14:15]
	global_load_dwordx4 v[64:67], v[26:27], off nt
	s_add_u32 s14, s14, 0x300000
	s_addc_u32 s15, s15, 0
	v_lshl_add_u64 v[26:27], v[8:9], 0, s[14:15]
	global_load_dwordx4 v[68:71], v[26:27], off nt
	s_add_u32 s14, s14, 0x300000
	s_addc_u32 s15, s15, 0
	v_lshl_add_u64 v[26:27], v[8:9], 0, s[14:15]
	global_load_dwordx4 v[72:75], v[26:27], off nt
	s_add_u32 s14, s14, 0x300000
	s_addc_u32 s15, s15, 0
	v_lshl_add_u64 v[26:27], v[8:9], 0, s[14:15]
	global_load_dwordx4 v[76:79], v[26:27], off nt
	s_add_u32 s14, s14, 0x300000
	s_addc_u32 s15, s15, 0
	v_lshl_add_u64 v[26:27], v[8:9], 0, s[14:15]
	global_load_dwordx4 v[84:87], v[26:27], off nt
	s_add_u32 s14, s14, 0x300000
	s_addc_u32 s15, s15, 0
	v_lshl_add_u64 v[26:27], v[8:9], 0, s[14:15]
	global_load_dwordx4 v[88:91], v[26:27], off nt
	s_add_u32 s14, s14, 0x300000
	s_addc_u32 s15, s15, 0
	v_lshl_add_u64 v[26:27], v[8:9], 0, s[14:15]
	global_load_dwordx4 v[92:95], v[26:27], off nt
	s_add_u32 s14, s14, 0x300000
	s_addc_u32 s15, s15, 0
	v_lshl_add_u64 v[26:27], v[8:9], 0, s[14:15]
	global_load_dwordx4 v[100:103], v[26:27], off nt
	s_add_u32 s14, s14, 0x300000
	s_addc_u32 s15, s15, 0
	v_lshl_add_u64 v[26:27], v[8:9], 0, s[14:15]
	global_load_dwordx4 v[104:107], v[26:27], off nt
	s_add_u32 s14, s14, 0x300000
	s_addc_u32 s15, s15, 0
	v_lshl_add_u64 v[26:27], v[8:9], 0, s[14:15]
	global_load_dwordx4 v[108:111], v[26:27], off nt
	s_add_u32 s14, s14, 0x300000
	s_addc_u32 s15, s15, 0
	v_lshl_add_u64 v[26:27], v[8:9], 0, s[14:15]
	global_load_dwordx4 v[112:115], v[26:27], off nt
	s_add_u32 s14, s14, 0x300000
	s_addc_u32 s15, s15, 0
	v_lshl_add_u64 v[26:27], v[8:9], 0, s[14:15]
	global_load_dwordx4 v[116:119], v[26:27], off nt
	s_add_u32 s14, s14, 0x300000
	s_addc_u32 s15, s15, 0
	v_lshl_add_u64 v[26:27], v[8:9], 0, s[14:15]
	global_load_dwordx4 v[120:123], v[26:27], off nt
	s_add_u32 s14, s14, 0x300000
	s_addc_u32 s15, s15, 0
	v_lshl_add_u64 v[26:27], v[8:9], 0, s[14:15]
	global_load_dwordx4 v[124:127], v[26:27], off nt
	s_add_u32 s14, s14, 0x300000
	s_addc_u32 s15, s15, 0
	v_lshl_add_u64 v[26:27], v[8:9], 0, s[14:15]
	global_load_dwordx4 v[128:131], v[26:27], off nt
	s_add_u32 s14, s14, 0x300000
	s_addc_u32 s15, s15, 0
	v_lshl_add_u64 v[26:27], v[8:9], 0, s[14:15]
	global_load_dwordx4 v[132:135], v[26:27], off nt
	s_add_u32 s14, s14, 0x300000
	s_addc_u32 s15, s15, 0
	v_lshl_add_u64 v[26:27], v[8:9], 0, s[14:15]
	global_load_dwordx4 v[136:139], v[26:27], off nt
	s_add_u32 s14, s14, 0x300000
	s_addc_u32 s15, s15, 0
	v_lshl_add_u64 v[26:27], v[8:9], 0, s[14:15]
	global_load_dwordx4 v[140:143], v[26:27], off nt
	s_add_u32 s14, s14, 0x300000
	s_addc_u32 s15, s15, 0
	v_lshl_add_u64 v[26:27], v[8:9], 0, s[14:15]
	global_load_dwordx4 v[144:147], v[26:27], off nt
	s_add_u32 s14, s14, 0x300000
	s_addc_u32 s15, s15, 0
	v_lshl_add_u64 v[26:27], v[8:9], 0, s[14:15]
	global_load_dwordx4 v[148:151], v[26:27], off nt
	s_add_u32 s14, s14, 0x300000
	s_addc_u32 s15, s15, 0
	v_lshl_add_u64 v[26:27], v[8:9], 0, s[14:15]
	global_load_dwordx4 v[152:155], v[26:27], off nt
	s_add_u32 s14, s14, 0x300000
	s_addc_u32 s15, s15, 0
	v_lshl_add_u64 v[26:27], v[8:9], 0, s[14:15]
	global_load_dwordx4 v[156:159], v[26:27], off nt
	s_add_u32 s14, s14, 0x300000
	s_addc_u32 s15, s15, 0
	v_lshl_add_u64 v[26:27], v[8:9], 0, s[14:15]
	global_load_dwordx4 v[160:163], v[26:27], off nt
	s_add_u32 s14, s14, 0x300000
	s_addc_u32 s15, s15, 0
	v_lshl_add_u64 v[26:27], v[8:9], 0, s[14:15]
	global_load_dwordx4 v[168:171], v[26:27], off nt
	s_add_u32 s14, s14, 0x300000
	s_addc_u32 s15, s15, 0
	v_lshl_add_u64 v[26:27], v[8:9], 0, s[14:15]
	global_load_dwordx4 v[172:175], v[26:27], off nt
	s_add_u32 s14, s14, 0x300000
	s_addc_u32 s15, s15, 0
	v_lshl_add_u64 v[26:27], v[8:9], 0, s[14:15]
	global_load_dwordx4 v[176:179], v[26:27], off nt
	s_add_u32 s14, s14, 0x300000
	s_addc_u32 s15, s15, 0
	v_lshl_add_u64 v[26:27], v[8:9], 0, s[14:15]
	global_load_dwordx4 v[180:183], v[26:27], off nt
	s_add_u32 s14, s14, 0x300000
	s_addc_u32 s15, s15, 0
	v_lshl_add_u64 v[26:27], v[8:9], 0, s[14:15]
	global_load_dwordx4 v[184:187], v[26:27], off nt
	s_add_u32 s14, s14, 0x300000
	s_addc_u32 s15, s15, 0
	v_lshl_add_u64 v[26:27], v[8:9], 0, s[14:15]
	global_load_dwordx4 v[188:191], v[26:27], off nt
	s_add_u32 s14, s14, 0x300000
	s_addc_u32 s15, s15, 0
	v_lshl_add_u64 v[26:27], v[8:9], 0, s[14:15]
	global_load_dwordx4 v[192:195], v[26:27], off nt
	s_add_u32 s14, s14, 0x300000
	s_addc_u32 s15, s15, 0
	v_lshl_add_u64 v[26:27], v[8:9], 0, s[14:15]
	global_load_dwordx4 v[196:199], v[26:27], off nt
	s_add_u32 s14, s14, 0x300000
	s_addc_u32 s15, s15, 0
	ds_read2_b32 v[50:51], v48 offset1:1
	ds_read2_b32 v[52:53], v48 offset0:2 offset1:3
	ds_read2_b32 v[54:55], v48 offset0:4 offset1:5
	ds_read2_b32 v[56:57], v48 offset0:6 offset1:7
	ds_read_b32 v58, v48 offset:32
	v_add_u32_e32 v27, 0x900, v48
	ds_read2_b32 v[200:201], v27 offset1:1
	ds_read2_b32 v[202:203], v27 offset0:2 offset1:3
	ds_read2_b32 v[204:205], v27 offset0:4 offset1:5
	ds_read2_b32 v[206:207], v27 offset0:6 offset1:7
	ds_read_b32 v208, v27 offset:32
	s_waitcnt vmcnt(31) lgkmcnt(5)
; __device__ __forceinline__ void ada_phase(LAS unsigned char* lds, const float* c, const float* c_ctx, const float* ada_w, const float* ada_b, float* mods, int G, int bid, int tid, int item0, int item1) {
;     ...
; #pragma unroll 16
;         for (int i = 0; i < 32; ++i) { const int k = ks + 64 * i; const f32x4 w = *(const f32x4*)(wp + (size_t)k * MODW);
; #pragma unroll
;             for (int r = 0; r < 9; ++r) acc[r] += w * sT[k * 9 + r]; }
	v_pk_fma_f32 v[46:47], v[60:61], v[50:51], v[46:47] op_sel_hi:[1,0,1]
	v_pk_fma_f32 v[44:45], v[62:63], v[50:51], v[44:45] op_sel_hi:[1,0,1]
	v_pk_fma_f32 v[42:43], v[60:61], v[50:51], v[42:43] op_sel:[0,1,0]
	v_pk_fma_f32 v[40:41], v[62:63], v[50:51], v[40:41] op_sel:[0,1,0]
	v_pk_fma_f32 v[38:39], v[60:61], v[52:53], v[38:39] op_sel_hi:[1,0,1]
	v_pk_fma_f32 v[36:37], v[62:63], v[52:53], v[36:37] op_sel_hi:[1,0,1]
	v_pk_fma_f32 v[34:35], v[60:61], v[52:53], v[34:35] op_sel:[0,1,0]
	v_pk_fma_f32 v[32:33], v[62:63], v[52:53], v[32:33] op_sel:[0,1,0]
	v_pk_fma_f32 v[30:31], v[60:61], v[54:55], v[30:31] op_sel_hi:[1,0,1]
	v_pk_fma_f32 v[28:29], v[62:63], v[54:55], v[28:29] op_sel_hi:[1,0,1]
	v_pk_fma_f32 v[24:25], v[60:61], v[54:55], v[24:25] op_sel:[0,1,0]
	v_pk_fma_f32 v[22:23], v[62:63], v[54:55], v[22:23] op_sel:[0,1,0]
	v_pk_fma_f32 v[20:21], v[60:61], v[56:57], v[20:21] op_sel_hi:[1,0,1]
	v_pk_fma_f32 v[18:19], v[62:63], v[56:57], v[18:19] op_sel_hi:[1,0,1]
	v_pk_fma_f32 v[16:17], v[60:61], v[56:57], v[16:17] op_sel:[0,1,0]
	v_pk_fma_f32 v[14:15], v[62:63], v[56:57], v[14:15] op_sel:[0,1,0]
	v_pk_fma_f32 v[12:13], v[60:61], v[58:59], v[12:13] op_sel_hi:[1,0,1]
	v_pk_fma_f32 v[10:11], v[62:63], v[58:59], v[10:11] op_sel_hi:[1,0,1]
	v_add_u32_e32 v27, 0x1200, v48
	ds_read2_b32 v[50:51], v27 offset1:1
	ds_read2_b32 v[52:53], v27 offset0:2 offset1:3
	ds_read2_b32 v[54:55], v27 offset0:4 offset1:5
	ds_read2_b32 v[56:57], v27 offset0:6 offset1:7
	ds_read_b32 v58, v27 offset:32
	s_waitcnt vmcnt(30) lgkmcnt(5)
	v_pk_fma_f32 v[46:47], v[64:65], v[200:201], v[46:47] op_sel_hi:[1,0,1]
	v_pk_fma_f32 v[44:45], v[66:67], v[200:201], v[44:45] op_sel_hi:[1,0,1]
	v_pk_fma_f32 v[42:43], v[64:65], v[200:201], v[42:43] op_sel:[0,1,0]
	v_pk_fma_f32 v[40:41], v[66:67], v[200:201], v[40:41] op_sel:[0,1,0]
	v_pk_fma_f32 v[38:39], v[64:65], v[202:203], v[38:39] op_sel_hi:[1,0,1]
	v_pk_fma_f32 v[36:37], v[66:67], v[202:203], v[36:37] op_sel_hi:[1,0,1]
	v_pk_fma_f32 v[34:35], v[64:65], v[202:203], v[34:35] op_sel:[0,1,0]
	v_pk_fma_f32 v[32:33], v[66:67], v[202:203], v[32:33] op_sel:[0,1,0]
	v_pk_fma_f32 v[30:31], v[64:65], v[204:205], v[30:31] op_sel_hi:[1,0,1]
	v_pk_fma_f32 v[28:29], v[66:67], v[204:205], v[28:29] op_sel_hi:[1,0,1]
	v_pk_fma_f32 v[24:25], v[64:65], v[204:205], v[24:25] op_sel:[0,1,0]
	v_pk_fma_f32 v[22:23], v[66:67], v[204:205], v[22:23] op_sel:[0,1,0]
	v_pk_fma_f32 v[20:21], v[64:65], v[206:207], v[20:21] op_sel_hi:[1,0,1]
	v_pk_fma_f32 v[18:19], v[66:67], v[206:207], v[18:19] op_sel_hi:[1,0,1]
	v_pk_fma_f32 v[16:17], v[64:65], v[206:207], v[16:17] op_sel:[0,1,0]
	v_pk_fma_f32 v[14:15], v[66:67], v[206:207], v[14:15] op_sel:[0,1,0]
	v_pk_fma_f32 v[12:13], v[64:65], v[208:209], v[12:13] op_sel_hi:[1,0,1]
	v_pk_fma_f32 v[10:11], v[66:67], v[208:209], v[10:11] op_sel_hi:[1,0,1]
	v_add_u32_e32 v27, 0x1b00, v48
	ds_read2_b32 v[200:201], v27 offset1:1
	ds_read2_b32 v[202:203], v27 offset0:2 offset1:3
	ds_read2_b32 v[204:205], v27 offset0:4 offset1:5
	ds_read2_b32 v[206:207], v27 offset0:6 offset1:7
	ds_read_b32 v208, v27 offset:32
	s_waitcnt vmcnt(29) lgkmcnt(5)
	v_pk_fma_f32 v[46:47], v[68:69], v[50:51], v[46:47] op_sel_hi:[1,0,1]
	v_pk_fma_f32 v[44:45], v[70:71], v[50:51], v[44:45] op_sel_hi:[1,0,1]
	v_pk_fma_f32 v[42:43], v[68:69], v[50:51], v[42:43] op_sel:[0,1,0]
	v_pk_fma_f32 v[40:41], v[70:71], v[50:51], v[40:41] op_sel:[0,1,0]
	v_pk_fma_f32 v[38:39], v[68:69], v[52:53], v[38:39] op_sel_hi:[1,0,1]
	v_pk_fma_f32 v[36:37], v[70:71], v[52:53], v[36:37] op_sel_hi:[1,0,1]
	v_pk_fma_f32 v[34:35], v[68:69], v[52:53], v[34:35] op_sel:[0,1,0]
	v_pk_fma_f32 v[32:33], v[70:71], v[52:53], v[32:33] op_sel:[0,1,0]
	v_pk_fma_f32 v[30:31], v[68:69], v[54:55], v[30:31] op_sel_hi:[1,0,1]
	v_pk_fma_f32 v[28:29], v[70:71], v[54:55], v[28:29] op_sel_hi:[1,0,1]
	v_pk_fma_f32 v[24:25], v[68:69], v[54:55], v[24:25] op_sel:[0,1,0]
	v_pk_fma_f32 v[22:23], v[70:71], v[54:55], v[22:23] op_sel:[0,1,0]
	v_pk_fma_f32 v[20:21], v[68:69], v[56:57], v[20:21] op_sel_hi:[1,0,1]
	v_pk_fma_f32 v[18:19], v[70:71], v[56:57], v[18:19] op_sel_hi:[1,0,1]
	v_pk_fma_f32 v[16:17], v[68:69], v[56:57], v[16:17] op_sel:[0,1,0]
	v_pk_fma_f32 v[14:15], v[70:71], v[56:57], v[14:15] op_sel:[0,1,0]
	v_pk_fma_f32 v[12:13], v[68:69], v[58:59], v[12:13] op_sel_hi:[1,0,1]
	v_pk_fma_f32 v[10:11], v[70:71], v[58:59], v[10:11] op_sel_hi:[1,0,1]
	v_add_u32_e32 v27, 0x2400, v48
	ds_read2_b32 v[50:51], v27 offset1:1
	ds_read2_b32 v[52:53], v27 offset0:2 offset1:3
	ds_read2_b32 v[54:55], v27 offset0:4 offset1:5
	ds_read2_b32 v[56:57], v27 offset0:6 offset1:7
	ds_read_b32 v58, v27 offset:32
	s_waitcnt vmcnt(28) lgkmcnt(5)
	v_pk_fma_f32 v[46:47], v[72:73], v[200:201], v[46:47] op_sel_hi:[1,0,1]
	v_pk_fma_f32 v[44:45], v[74:75], v[200:201], v[44:45] op_sel_hi:[1,0,1]
	v_pk_fma_f32 v[42:43], v[72:73], v[200:201], v[42:43] op_sel:[0,1,0]
	v_pk_fma_f32 v[40:41], v[74:75], v[200:201], v[40:41] op_sel:[0,1,0]
	v_pk_fma_f32 v[38:39], v[72:73], v[202:203], v[38:39] op_sel_hi:[1,0,1]
	v_pk_fma_f32 v[36:37], v[74:75], v[202:203], v[36:37] op_sel_hi:[1,0,1]
	v_pk_fma_f32 v[34:35], v[72:73], v[202:203], v[34:35] op_sel:[0,1,0]
	v_pk_fma_f32 v[32:33], v[74:75], v[202:203], v[32:33] op_sel:[0,1,0]
	v_pk_fma_f32 v[30:31], v[72:73], v[204:205], v[30:31] op_sel_hi:[1,0,1]
	v_pk_fma_f32 v[28:29], v[74:75], v[204:205], v[28:29] op_sel_hi:[1,0,1]
	v_pk_fma_f32 v[24:25], v[72:73], v[204:205], v[24:25] op_sel:[0,1,0]
	v_pk_fma_f32 v[22:23], v[74:75], v[204:205], v[22:23] op_sel:[0,1,0]
	v_pk_fma_f32 v[20:21], v[72:73], v[206:207], v[20:21] op_sel_hi:[1,0,1]
	v_pk_fma_f32 v[18:19], v[74:75], v[206:207], v[18:19] op_sel_hi:[1,0,1]
	v_pk_fma_f32 v[16:17], v[72:73], v[206:207], v[16:17] op_sel:[0,1,0]
	v_pk_fma_f32 v[14:15], v[74:75], v[206:207], v[14:15] op_sel:[0,1,0]
	v_pk_fma_f32 v[12:13], v[72:73], v[208:209], v[12:13] op_sel_hi:[1,0,1]
	v_pk_fma_f32 v[10:11], v[74:75], v[208:209], v[10:11] op_sel_hi:[1,0,1]
	v_add_u32_e32 v27, 0x2d00, v48
	ds_read2_b32 v[200:201], v27 offset1:1
	ds_read2_b32 v[202:203], v27 offset0:2 offset1:3
	ds_read2_b32 v[204:205], v27 offset0:4 offset1:5
	ds_read2_b32 v[206:207], v27 offset0:6 offset1:7
	ds_read_b32 v208, v27 offset:32
	s_waitcnt vmcnt(27) lgkmcnt(5)
; __device__ __forceinline__ void ada_phase(LAS unsigned char* lds, const float* c, const float* c_ctx, const float* ada_w, const float* ada_b, float* mods, int G, int bid, int tid, int item0, int item1) {
;     ...
; #pragma unroll 16
;         for (int i = 0; i < 32; ++i) { const int k = ks + 64 * i; const f32x4 w = *(const f32x4*)(wp + (size_t)k * MODW);
; #pragma unroll
;             for (int r = 0; r < 9; ++r) acc[r] += w * sT[k * 9 + r]; }
	v_pk_fma_f32 v[46:47], v[76:77], v[50:51], v[46:47] op_sel_hi:[1,0,1]
	v_pk_fma_f32 v[44:45], v[78:79], v[50:51], v[44:45] op_sel_hi:[1,0,1]
	v_pk_fma_f32 v[42:43], v[76:77], v[50:51], v[42:43] op_sel:[0,1,0]
	v_pk_fma_f32 v[40:41], v[78:79], v[50:51], v[40:41] op_sel:[0,1,0]
	v_pk_fma_f32 v[38:39], v[76:77], v[52:53], v[38:39] op_sel_hi:[1,0,1]
	v_pk_fma_f32 v[36:37], v[78:79], v[52:53], v[36:37] op_sel_hi:[1,0,1]
	v_pk_fma_f32 v[34:35], v[76:77], v[52:53], v[34:35] op_sel:[0,1,0]
	v_pk_fma_f32 v[32:33], v[78:79], v[52:53], v[32:33] op_sel:[0,1,0]
	v_pk_fma_f32 v[30:31], v[76:77], v[54:55], v[30:31] op_sel_hi:[1,0,1]
	v_pk_fma_f32 v[28:29], v[78:79], v[54:55], v[28:29] op_sel_hi:[1,0,1]
	v_pk_fma_f32 v[24:25], v[76:77], v[54:55], v[24:25] op_sel:[0,1,0]
	v_pk_fma_f32 v[22:23], v[78:79], v[54:55], v[22:23] op_sel:[0,1,0]
	v_pk_fma_f32 v[20:21], v[76:77], v[56:57], v[20:21] op_sel_hi:[1,0,1]
	v_pk_fma_f32 v[18:19], v[78:79], v[56:57], v[18:19] op_sel_hi:[1,0,1]
	v_pk_fma_f32 v[16:17], v[76:77], v[56:57], v[16:17] op_sel:[0,1,0]
	v_pk_fma_f32 v[14:15], v[78:79], v[56:57], v[14:15] op_sel:[0,1,0]
	v_pk_fma_f32 v[12:13], v[76:77], v[58:59], v[12:13] op_sel_hi:[1,0,1]
	v_pk_fma_f32 v[10:11], v[78:79], v[58:59], v[10:11] op_sel_hi:[1,0,1]
	v_add_u32_e32 v27, 0x3600, v48
	ds_read2_b32 v[50:51], v27 offset1:1
	ds_read2_b32 v[52:53], v27 offset0:2 offset1:3
	ds_read2_b32 v[54:55], v27 offset0:4 offset1:5
	ds_read2_b32 v[56:57], v27 offset0:6 offset1:7
	ds_read_b32 v58, v27 offset:32
	s_waitcnt vmcnt(26) lgkmcnt(5)
	v_pk_fma_f32 v[46:47], v[84:85], v[200:201], v[46:47] op_sel_hi:[1,0,1]
	v_pk_fma_f32 v[44:45], v[86:87], v[200:201], v[44:45] op_sel_hi:[1,0,1]
	v_pk_fma_f32 v[42:43], v[84:85], v[200:201], v[42:43] op_sel:[0,1,0]
	v_pk_fma_f32 v[40:41], v[86:87], v[200:201], v[40:41] op_sel:[0,1,0]
	v_pk_fma_f32 v[38:39], v[84:85], v[202:203], v[38:39] op_sel_hi:[1,0,1]
	v_pk_fma_f32 v[36:37], v[86:87], v[202:203], v[36:37] op_sel_hi:[1,0,1]
	v_pk_fma_f32 v[34:35], v[84:85], v[202:203], v[34:35] op_sel:[0,1,0]
	v_pk_fma_f32 v[32:33], v[86:87], v[202:203], v[32:33] op_sel:[0,1,0]
	v_pk_fma_f32 v[30:31], v[84:85], v[204:205], v[30:31] op_sel_hi:[1,0,1]
	v_pk_fma_f32 v[28:29], v[86:87], v[204:205], v[28:29] op_sel_hi:[1,0,1]
	v_pk_fma_f32 v[24:25], v[84:85], v[204:205], v[24:25] op_sel:[0,1,0]
	v_pk_fma_f32 v[22:23], v[86:87], v[204:205], v[22:23] op_sel:[0,1,0]
	v_pk_fma_f32 v[20:21], v[84:85], v[206:207], v[20:21] op_sel_hi:[1,0,1]
	v_pk_fma_f32 v[18:19], v[86:87], v[206:207], v[18:19] op_sel_hi:[1,0,1]
	v_pk_fma_f32 v[16:17], v[84:85], v[206:207], v[16:17] op_sel:[0,1,0]
	v_pk_fma_f32 v[14:15], v[86:87], v[206:207], v[14:15] op_sel:[0,1,0]
	v_pk_fma_f32 v[12:13], v[84:85], v[208:209], v[12:13] op_sel_hi:[1,0,1]
	v_pk_fma_f32 v[10:11], v[86:87], v[208:209], v[10:11] op_sel_hi:[1,0,1]
	v_add_u32_e32 v27, 0x3f00, v48
	ds_read2_b32 v[200:201], v27 offset1:1
	ds_read2_b32 v[202:203], v27 offset0:2 offset1:3
	ds_read2_b32 v[204:205], v27 offset0:4 offset1:5
	ds_read2_b32 v[206:207], v27 offset0:6 offset1:7
	ds_read_b32 v208, v27 offset:32
	s_waitcnt vmcnt(25) lgkmcnt(5)
	v_pk_fma_f32 v[46:47], v[88:89], v[50:51], v[46:47] op_sel_hi:[1,0,1]
	v_pk_fma_f32 v[44:45], v[90:91], v[50:51], v[44:45] op_sel_hi:[1,0,1]
	v_pk_fma_f32 v[42:43], v[88:89], v[50:51], v[42:43] op_sel:[0,1,0]
	v_pk_fma_f32 v[40:41], v[90:91], v[50:51], v[40:41] op_sel:[0,1,0]
	v_pk_fma_f32 v[38:39], v[88:89], v[52:53], v[38:39] op_sel_hi:[1,0,1]
	v_pk_fma_f32 v[36:37], v[90:91], v[52:53], v[36:37] op_sel_hi:[1,0,1]
	v_pk_fma_f32 v[34:35], v[88:89], v[52:53], v[34:35] op_sel:[0,1,0]
	v_pk_fma_f32 v[32:33], v[90:91], v[52:53], v[32:33] op_sel:[0,1,0]
	v_pk_fma_f32 v[30:31], v[88:89], v[54:55], v[30:31] op_sel_hi:[1,0,1]
	v_pk_fma_f32 v[28:29], v[90:91], v[54:55], v[28:29] op_sel_hi:[1,0,1]
	v_pk_fma_f32 v[24:25], v[88:89], v[54:55], v[24:25] op_sel:[0,1,0]
	v_pk_fma_f32 v[22:23], v[90:91], v[54:55], v[22:23] op_sel:[0,1,0]
	v_pk_fma_f32 v[20:21], v[88:89], v[56:57], v[20:21] op_sel_hi:[1,0,1]
	v_pk_fma_f32 v[18:19], v[90:91], v[56:57], v[18:19] op_sel_hi:[1,0,1]
	v_pk_fma_f32 v[16:17], v[88:89], v[56:57], v[16:17] op_sel:[0,1,0]
	v_pk_fma_f32 v[14:15], v[90:91], v[56:57], v[14:15] op_sel:[0,1,0]
	v_pk_fma_f32 v[12:13], v[88:89], v[58:59], v[12:13] op_sel_hi:[1,0,1]
	v_pk_fma_f32 v[10:11], v[90:91], v[58:59], v[10:11] op_sel_hi:[1,0,1]
	v_add_u32_e32 v27, 0x4800, v48
	ds_read2_b32 v[50:51], v27 offset1:1
	ds_read2_b32 v[52:53], v27 offset0:2 offset1:3
	ds_read2_b32 v[54:55], v27 offset0:4 offset1:5
	ds_read2_b32 v[56:57], v27 offset0:6 offset1:7
	ds_read_b32 v58, v27 offset:32
	s_waitcnt vmcnt(24) lgkmcnt(5)
	v_pk_fma_f32 v[46:47], v[92:93], v[200:201], v[46:47] op_sel_hi:[1,0,1]
	v_pk_fma_f32 v[44:45], v[94:95], v[200:201], v[44:45] op_sel_hi:[1,0,1]
	v_pk_fma_f32 v[42:43], v[92:93], v[200:201], v[42:43] op_sel:[0,1,0]
	v_pk_fma_f32 v[40:41], v[94:95], v[200:201], v[40:41] op_sel:[0,1,0]
	v_pk_fma_f32 v[38:39], v[92:93], v[202:203], v[38:39] op_sel_hi:[1,0,1]
	v_pk_fma_f32 v[36:37], v[94:95], v[202:203], v[36:37] op_sel_hi:[1,0,1]
	v_pk_fma_f32 v[34:35], v[92:93], v[202:203], v[34:35] op_sel:[0,1,0]
	v_pk_fma_f32 v[32:33], v[94:95], v[202:203], v[32:33] op_sel:[0,1,0]
	v_pk_fma_f32 v[30:31], v[92:93], v[204:205], v[30:31] op_sel_hi:[1,0,1]
	v_pk_fma_f32 v[28:29], v[94:95], v[204:205], v[28:29] op_sel_hi:[1,0,1]
	v_pk_fma_f32 v[24:25], v[92:93], v[204:205], v[24:25] op_sel:[0,1,0]
	v_pk_fma_f32 v[22:23], v[94:95], v[204:205], v[22:23] op_sel:[0,1,0]
	v_pk_fma_f32 v[20:21], v[92:93], v[206:207], v[20:21] op_sel_hi:[1,0,1]
	v_pk_fma_f32 v[18:19], v[94:95], v[206:207], v[18:19] op_sel_hi:[1,0,1]
	v_pk_fma_f32 v[16:17], v[92:93], v[206:207], v[16:17] op_sel:[0,1,0]
	v_pk_fma_f32 v[14:15], v[94:95], v[206:207], v[14:15] op_sel:[0,1,0]
	v_pk_fma_f32 v[12:13], v[92:93], v[208:209], v[12:13] op_sel_hi:[1,0,1]
	v_pk_fma_f32 v[10:11], v[94:95], v[208:209], v[10:11] op_sel_hi:[1,0,1]
	v_add_u32_e32 v27, 0x5100, v48
	ds_read2_b32 v[200:201], v27 offset1:1
	ds_read2_b32 v[202:203], v27 offset0:2 offset1:3
	ds_read2_b32 v[204:205], v27 offset0:4 offset1:5
	ds_read2_b32 v[206:207], v27 offset0:6 offset1:7
	ds_read_b32 v208, v27 offset:32
	s_waitcnt vmcnt(23) lgkmcnt(5)
; __device__ __forceinline__ void ada_phase(LAS unsigned char* lds, const float* c, const float* c_ctx, const float* ada_w, const float* ada_b, float* mods, int G, int bid, int tid, int item0, int item1) {
;     ...
; #pragma unroll 16
;         for (int i = 0; i < 32; ++i) { const int k = ks + 64 * i; const f32x4 w = *(const f32x4*)(wp + (size_t)k * MODW);
; #pragma unroll
;             for (int r = 0; r < 9; ++r) acc[r] += w * sT[k * 9 + r]; }
	v_pk_fma_f32 v[46:47], v[100:101], v[50:51], v[46:47] op_sel_hi:[1,0,1]
	v_pk_fma_f32 v[44:45], v[102:103], v[50:51], v[44:45] op_sel_hi:[1,0,1]
	v_pk_fma_f32 v[42:43], v[100:101], v[50:51], v[42:43] op_sel:[0,1,0]
	v_pk_fma_f32 v[40:41], v[102:103], v[50:51], v[40:41] op_sel:[0,1,0]
	v_pk_fma_f32 v[38:39], v[100:101], v[52:53], v[38:39] op_sel_hi:[1,0,1]
	v_pk_fma_f32 v[36:37], v[102:103], v[52:53], v[36:37] op_sel_hi:[1,0,1]
	v_pk_fma_f32 v[34:35], v[100:101], v[52:53], v[34:35] op_sel:[0,1,0]
	v_pk_fma_f32 v[32:33], v[102:103], v[52:53], v[32:33] op_sel:[0,1,0]
	v_pk_fma_f32 v[30:31], v[100:101], v[54:55], v[30:31] op_sel_hi:[1,0,1]
	v_pk_fma_f32 v[28:29], v[102:103], v[54:55], v[28:29] op_sel_hi:[1,0,1]
	v_pk_fma_f32 v[24:25], v[100:101], v[54:55], v[24:25] op_sel:[0,1,0]
	v_pk_fma_f32 v[22:23], v[102:103], v[54:55], v[22:23] op_sel:[0,1,0]
	v_pk_fma_f32 v[20:21], v[100:101], v[56:57], v[20:21] op_sel_hi:[1,0,1]
	v_pk_fma_f32 v[18:19], v[102:103], v[56:57], v[18:19] op_sel_hi:[1,0,1]
	v_pk_fma_f32 v[16:17], v[100:101], v[56:57], v[16:17] op_sel:[0,1,0]
	v_pk_fma_f32 v[14:15], v[102:103], v[56:57], v[14:15] op_sel:[0,1,0]
	v_pk_fma_f32 v[12:13], v[100:101], v[58:59], v[12:13] op_sel_hi:[1,0,1]
	v_pk_fma_f32 v[10:11], v[102:103], v[58:59], v[10:11] op_sel_hi:[1,0,1]
	v_add_u32_e32 v27, 0x5a00, v48
	ds_read2_b32 v[50:51], v27 offset1:1
	ds_read2_b32 v[52:53], v27 offset0:2 offset1:3
	ds_read2_b32 v[54:55], v27 offset0:4 offset1:5
	ds_read2_b32 v[56:57], v27 offset0:6 offset1:7
	ds_read_b32 v58, v27 offset:32
	s_waitcnt vmcnt(22) lgkmcnt(5)
	v_pk_fma_f32 v[46:47], v[104:105], v[200:201], v[46:47] op_sel_hi:[1,0,1]
	v_pk_fma_f32 v[44:45], v[106:107], v[200:201], v[44:45] op_sel_hi:[1,0,1]
	v_pk_fma_f32 v[42:43], v[104:105], v[200:201], v[42:43] op_sel:[0,1,0]
	v_pk_fma_f32 v[40:41], v[106:107], v[200:201], v[40:41] op_sel:[0,1,0]
	v_pk_fma_f32 v[38:39], v[104:105], v[202:203], v[38:39] op_sel_hi:[1,0,1]
	v_pk_fma_f32 v[36:37], v[106:107], v[202:203], v[36:37] op_sel_hi:[1,0,1]
	v_pk_fma_f32 v[34:35], v[104:105], v[202:203], v[34:35] op_sel:[0,1,0]
	v_pk_fma_f32 v[32:33], v[106:107], v[202:203], v[32:33] op_sel:[0,1,0]
	v_pk_fma_f32 v[30:31], v[104:105], v[204:205], v[30:31] op_sel_hi:[1,0,1]
	v_pk_fma_f32 v[28:29], v[106:107], v[204:205], v[28:29] op_sel_hi:[1,0,1]
	v_pk_fma_f32 v[24:25], v[104:105], v[204:205], v[24:25] op_sel:[0,1,0]
	v_pk_fma_f32 v[22:23], v[106:107], v[204:205], v[22:23] op_sel:[0,1,0]
	v_pk_fma_f32 v[20:21], v[104:105], v[206:207], v[20:21] op_sel_hi:[1,0,1]
	v_pk_fma_f32 v[18:19], v[106:107], v[206:207], v[18:19] op_sel_hi:[1,0,1]
	v_pk_fma_f32 v[16:17], v[104:105], v[206:207], v[16:17] op_sel:[0,1,0]
	v_pk_fma_f32 v[14:15], v[106:107], v[206:207], v[14:15] op_sel:[0,1,0]
	v_pk_fma_f32 v[12:13], v[104:105], v[208:209], v[12:13] op_sel_hi:[1,0,1]
	v_pk_fma_f32 v[10:11], v[106:107], v[208:209], v[10:11] op_sel_hi:[1,0,1]
	v_add_u32_e32 v27, 0x6300, v48
	ds_read2_b32 v[200:201], v27 offset1:1
	ds_read2_b32 v[202:203], v27 offset0:2 offset1:3
	ds_read2_b32 v[204:205], v27 offset0:4 offset1:5
	ds_read2_b32 v[206:207], v27 offset0:6 offset1:7
	ds_read_b32 v208, v27 offset:32
	s_waitcnt vmcnt(21) lgkmcnt(5)
	v_pk_fma_f32 v[46:47], v[108:109], v[50:51], v[46:47] op_sel_hi:[1,0,1]
	v_pk_fma_f32 v[44:45], v[110:111], v[50:51], v[44:45] op_sel_hi:[1,0,1]
	v_pk_fma_f32 v[42:43], v[108:109], v[50:51], v[42:43] op_sel:[0,1,0]
	v_pk_fma_f32 v[40:41], v[110:111], v[50:51], v[40:41] op_sel:[0,1,0]
	v_pk_fma_f32 v[38:39], v[108:109], v[52:53], v[38:39] op_sel_hi:[1,0,1]
	v_pk_fma_f32 v[36:37], v[110:111], v[52:53], v[36:37] op_sel_hi:[1,0,1]
	v_pk_fma_f32 v[34:35], v[108:109], v[52:53], v[34:35] op_sel:[0,1,0]
	v_pk_fma_f32 v[32:33], v[110:111], v[52:53], v[32:33] op_sel:[0,1,0]
	v_pk_fma_f32 v[30:31], v[108:109], v[54:55], v[30:31] op_sel_hi:[1,0,1]
	v_pk_fma_f32 v[28:29], v[110:111], v[54:55], v[28:29] op_sel_hi:[1,0,1]
	v_pk_fma_f32 v[24:25], v[108:109], v[54:55], v[24:25] op_sel:[0,1,0]
	v_pk_fma_f32 v[22:23], v[110:111], v[54:55], v[22:23] op_sel:[0,1,0]
	v_pk_fma_f32 v[20:21], v[108:109], v[56:57], v[20:21] op_sel_hi:[1,0,1]
	v_pk_fma_f32 v[18:19], v[110:111], v[56:57], v[18:19] op_sel_hi:[1,0,1]
	v_pk_fma_f32 v[16:17], v[108:109], v[56:57], v[16:17] op_sel:[0,1,0]
	v_pk_fma_f32 v[14:15], v[110:111], v[56:57], v[14:15] op_sel:[0,1,0]
	v_pk_fma_f32 v[12:13], v[108:109], v[58:59], v[12:13] op_sel_hi:[1,0,1]
	v_pk_fma_f32 v[10:11], v[110:111], v[58:59], v[10:11] op_sel_hi:[1,0,1]
	v_add_u32_e32 v27, 0x6c00, v48
	ds_read2_b32 v[50:51], v27 offset1:1
	ds_read2_b32 v[52:53], v27 offset0:2 offset1:3
	ds_read2_b32 v[54:55], v27 offset0:4 offset1:5
	ds_read2_b32 v[56:57], v27 offset0:6 offset1:7
	ds_read_b32 v58, v27 offset:32
	s_waitcnt vmcnt(20) lgkmcnt(5)
	v_pk_fma_f32 v[46:47], v[112:113], v[200:201], v[46:47] op_sel_hi:[1,0,1]
	v_pk_fma_f32 v[44:45], v[114:115], v[200:201], v[44:45] op_sel_hi:[1,0,1]
	v_pk_fma_f32 v[42:43], v[112:113], v[200:201], v[42:43] op_sel:[0,1,0]
	v_pk_fma_f32 v[40:41], v[114:115], v[200:201], v[40:41] op_sel:[0,1,0]
	v_pk_fma_f32 v[38:39], v[112:113], v[202:203], v[38:39] op_sel_hi:[1,0,1]
	v_pk_fma_f32 v[36:37], v[114:115], v[202:203], v[36:37] op_sel_hi:[1,0,1]
	v_pk_fma_f32 v[34:35], v[112:113], v[202:203], v[34:35] op_sel:[0,1,0]
	v_pk_fma_f32 v[32:33], v[114:115], v[202:203], v[32:33] op_sel:[0,1,0]
	v_pk_fma_f32 v[30:31], v[112:113], v[204:205], v[30:31] op_sel_hi:[1,0,1]
	v_pk_fma_f32 v[28:29], v[114:115], v[204:205], v[28:29] op_sel_hi:[1,0,1]
	v_pk_fma_f32 v[24:25], v[112:113], v[204:205], v[24:25] op_sel:[0,1,0]
	v_pk_fma_f32 v[22:23], v[114:115], v[204:205], v[22:23] op_sel:[0,1,0]
	v_pk_fma_f32 v[20:21], v[112:113], v[206:207], v[20:21] op_sel_hi:[1,0,1]
	v_pk_fma_f32 v[18:19], v[114:115], v[206:207], v[18:19] op_sel_hi:[1,0,1]
	v_pk_fma_f32 v[16:17], v[112:113], v[206:207], v[16:17] op_sel:[0,1,0]
	v_pk_fma_f32 v[14:15], v[114:115], v[206:207], v[14:15] op_sel:[0,1,0]
	v_pk_fma_f32 v[12:13], v[112:113], v[208:209], v[12:13] op_sel_hi:[1,0,1]
	v_pk_fma_f32 v[10:11], v[114:115], v[208:209], v[10:11] op_sel_hi:[1,0,1]
	v_add_u32_e32 v27, 0x7500, v48
	ds_read2_b32 v[200:201], v27 offset1:1
	ds_read2_b32 v[202:203], v27 offset0:2 offset1:3
	ds_read2_b32 v[204:205], v27 offset0:4 offset1:5
	ds_read2_b32 v[206:207], v27 offset0:6 offset1:7
	ds_read_b32 v208, v27 offset:32
	s_waitcnt vmcnt(19) lgkmcnt(5)
; __device__ __forceinline__ void ada_phase(LAS unsigned char* lds, const float* c, const float* c_ctx, const float* ada_w, const float* ada_b, float* mods, int G, int bid, int tid, int item0, int item1) {
;     ...
; #pragma unroll 16
;         for (int i = 0; i < 32; ++i) { const int k = ks + 64 * i; const f32x4 w = *(const f32x4*)(wp + (size_t)k * MODW);
; #pragma unroll
;             for (int r = 0; r < 9; ++r) acc[r] += w * sT[k * 9 + r]; }
	v_pk_fma_f32 v[46:47], v[116:117], v[50:51], v[46:47] op_sel_hi:[1,0,1]
	v_pk_fma_f32 v[44:45], v[118:119], v[50:51], v[44:45] op_sel_hi:[1,0,1]
	v_pk_fma_f32 v[42:43], v[116:117], v[50:51], v[42:43] op_sel:[0,1,0]
	v_pk_fma_f32 v[40:41], v[118:119], v[50:51], v[40:41] op_sel:[0,1,0]
	v_pk_fma_f32 v[38:39], v[116:117], v[52:53], v[38:39] op_sel_hi:[1,0,1]
	v_pk_fma_f32 v[36:37], v[118:119], v[52:53], v[36:37] op_sel_hi:[1,0,1]
	v_pk_fma_f32 v[34:35], v[116:117], v[52:53], v[34:35] op_sel:[0,1,0]
	v_pk_fma_f32 v[32:33], v[118:119], v[52:53], v[32:33] op_sel:[0,1,0]
	v_pk_fma_f32 v[30:31], v[116:117], v[54:55], v[30:31] op_sel_hi:[1,0,1]
	v_pk_fma_f32 v[28:29], v[118:119], v[54:55], v[28:29] op_sel_hi:[1,0,1]
	v_pk_fma_f32 v[24:25], v[116:117], v[54:55], v[24:25] op_sel:[0,1,0]
	v_pk_fma_f32 v[22:23], v[118:119], v[54:55], v[22:23] op_sel:[0,1,0]
	v_pk_fma_f32 v[20:21], v[116:117], v[56:57], v[20:21] op_sel_hi:[1,0,1]
	v_pk_fma_f32 v[18:19], v[118:119], v[56:57], v[18:19] op_sel_hi:[1,0,1]
	v_pk_fma_f32 v[16:17], v[116:117], v[56:57], v[16:17] op_sel:[0,1,0]
	v_pk_fma_f32 v[14:15], v[118:119], v[56:57], v[14:15] op_sel:[0,1,0]
	v_pk_fma_f32 v[12:13], v[116:117], v[58:59], v[12:13] op_sel_hi:[1,0,1]
	v_pk_fma_f32 v[10:11], v[118:119], v[58:59], v[10:11] op_sel_hi:[1,0,1]
	v_add_u32_e32 v27, 0x7e00, v48
	ds_read2_b32 v[50:51], v27 offset1:1
	ds_read2_b32 v[52:53], v27 offset0:2 offset1:3
	ds_read2_b32 v[54:55], v27 offset0:4 offset1:5
	ds_read2_b32 v[56:57], v27 offset0:6 offset1:7
	ds_read_b32 v58, v27 offset:32
	s_waitcnt vmcnt(18) lgkmcnt(5)
	v_pk_fma_f32 v[46:47], v[120:121], v[200:201], v[46:47] op_sel_hi:[1,0,1]
	v_pk_fma_f32 v[44:45], v[122:123], v[200:201], v[44:45] op_sel_hi:[1,0,1]
	v_pk_fma_f32 v[42:43], v[120:121], v[200:201], v[42:43] op_sel:[0,1,0]
	v_pk_fma_f32 v[40:41], v[122:123], v[200:201], v[40:41] op_sel:[0,1,0]
	v_pk_fma_f32 v[38:39], v[120:121], v[202:203], v[38:39] op_sel_hi:[1,0,1]
	v_pk_fma_f32 v[36:37], v[122:123], v[202:203], v[36:37] op_sel_hi:[1,0,1]
	v_pk_fma_f32 v[34:35], v[120:121], v[202:203], v[34:35] op_sel:[0,1,0]
	v_pk_fma_f32 v[32:33], v[122:123], v[202:203], v[32:33] op_sel:[0,1,0]
	v_pk_fma_f32 v[30:31], v[120:121], v[204:205], v[30:31] op_sel_hi:[1,0,1]
	v_pk_fma_f32 v[28:29], v[122:123], v[204:205], v[28:29] op_sel_hi:[1,0,1]
	v_pk_fma_f32 v[24:25], v[120:121], v[204:205], v[24:25] op_sel:[0,1,0]
	v_pk_fma_f32 v[22:23], v[122:123], v[204:205], v[22:23] op_sel:[0,1,0]
	v_pk_fma_f32 v[20:21], v[120:121], v[206:207], v[20:21] op_sel_hi:[1,0,1]
	v_pk_fma_f32 v[18:19], v[122:123], v[206:207], v[18:19] op_sel_hi:[1,0,1]
	v_pk_fma_f32 v[16:17], v[120:121], v[206:207], v[16:17] op_sel:[0,1,0]
	v_pk_fma_f32 v[14:15], v[122:123], v[206:207], v[14:15] op_sel:[0,1,0]
	v_pk_fma_f32 v[12:13], v[120:121], v[208:209], v[12:13] op_sel_hi:[1,0,1]
	v_pk_fma_f32 v[10:11], v[122:123], v[208:209], v[10:11] op_sel_hi:[1,0,1]
	v_add_u32_e32 v27, 0x8700, v48
	ds_read2_b32 v[200:201], v27 offset1:1
	ds_read2_b32 v[202:203], v27 offset0:2 offset1:3
	ds_read2_b32 v[204:205], v27 offset0:4 offset1:5
	ds_read2_b32 v[206:207], v27 offset0:6 offset1:7
	ds_read_b32 v208, v27 offset:32
	s_waitcnt vmcnt(17) lgkmcnt(5)
	v_pk_fma_f32 v[46:47], v[124:125], v[50:51], v[46:47] op_sel_hi:[1,0,1]
	v_pk_fma_f32 v[44:45], v[126:127], v[50:51], v[44:45] op_sel_hi:[1,0,1]
	v_pk_fma_f32 v[42:43], v[124:125], v[50:51], v[42:43] op_sel:[0,1,0]
	v_pk_fma_f32 v[40:41], v[126:127], v[50:51], v[40:41] op_sel:[0,1,0]
	v_pk_fma_f32 v[38:39], v[124:125], v[52:53], v[38:39] op_sel_hi:[1,0,1]
	v_pk_fma_f32 v[36:37], v[126:127], v[52:53], v[36:37] op_sel_hi:[1,0,1]
	v_pk_fma_f32 v[34:35], v[124:125], v[52:53], v[34:35] op_sel:[0,1,0]
	v_pk_fma_f32 v[32:33], v[126:127], v[52:53], v[32:33] op_sel:[0,1,0]
	v_pk_fma_f32 v[30:31], v[124:125], v[54:55], v[30:31] op_sel_hi:[1,0,1]
	v_pk_fma_f32 v[28:29], v[126:127], v[54:55], v[28:29] op_sel_hi:[1,0,1]
	v_pk_fma_f32 v[24:25], v[124:125], v[54:55], v[24:25] op_sel:[0,1,0]
	v_pk_fma_f32 v[22:23], v[126:127], v[54:55], v[22:23] op_sel:[0,1,0]
	v_pk_fma_f32 v[20:21], v[124:125], v[56:57], v[20:21] op_sel_hi:[1,0,1]
	v_pk_fma_f32 v[18:19], v[126:127], v[56:57], v[18:19] op_sel_hi:[1,0,1]
	v_pk_fma_f32 v[16:17], v[124:125], v[56:57], v[16:17] op_sel:[0,1,0]
	v_pk_fma_f32 v[14:15], v[126:127], v[56:57], v[14:15] op_sel:[0,1,0]
	v_pk_fma_f32 v[12:13], v[124:125], v[58:59], v[12:13] op_sel_hi:[1,0,1]
	v_pk_fma_f32 v[10:11], v[126:127], v[58:59], v[10:11] op_sel_hi:[1,0,1]
	v_add_u32_e32 v27, 0x9000, v48
	ds_read2_b32 v[50:51], v27 offset1:1
	ds_read2_b32 v[52:53], v27 offset0:2 offset1:3
	ds_read2_b32 v[54:55], v27 offset0:4 offset1:5
	ds_read2_b32 v[56:57], v27 offset0:6 offset1:7
	ds_read_b32 v58, v27 offset:32
	s_waitcnt vmcnt(16) lgkmcnt(5)
	v_pk_fma_f32 v[46:47], v[128:129], v[200:201], v[46:47] op_sel_hi:[1,0,1]
	v_pk_fma_f32 v[44:45], v[130:131], v[200:201], v[44:45] op_sel_hi:[1,0,1]
	v_pk_fma_f32 v[42:43], v[128:129], v[200:201], v[42:43] op_sel:[0,1,0]
	v_pk_fma_f32 v[40:41], v[130:131], v[200:201], v[40:41] op_sel:[0,1,0]
	v_pk_fma_f32 v[38:39], v[128:129], v[202:203], v[38:39] op_sel_hi:[1,0,1]
	v_pk_fma_f32 v[36:37], v[130:131], v[202:203], v[36:37] op_sel_hi:[1,0,1]
	v_pk_fma_f32 v[34:35], v[128:129], v[202:203], v[34:35] op_sel:[0,1,0]
	v_pk_fma_f32 v[32:33], v[130:131], v[202:203], v[32:33] op_sel:[0,1,0]
	v_pk_fma_f32 v[30:31], v[128:129], v[204:205], v[30:31] op_sel_hi:[1,0,1]
	v_pk_fma_f32 v[28:29], v[130:131], v[204:205], v[28:29] op_sel_hi:[1,0,1]
	v_pk_fma_f32 v[24:25], v[128:129], v[204:205], v[24:25] op_sel:[0,1,0]
	v_pk_fma_f32 v[22:23], v[130:131], v[204:205], v[22:23] op_sel:[0,1,0]
	v_pk_fma_f32 v[20:21], v[128:129], v[206:207], v[20:21] op_sel_hi:[1,0,1]
	v_pk_fma_f32 v[18:19], v[130:131], v[206:207], v[18:19] op_sel_hi:[1,0,1]
	v_pk_fma_f32 v[16:17], v[128:129], v[206:207], v[16:17] op_sel:[0,1,0]
	v_pk_fma_f32 v[14:15], v[130:131], v[206:207], v[14:15] op_sel:[0,1,0]
	v_pk_fma_f32 v[12:13], v[128:129], v[208:209], v[12:13] op_sel_hi:[1,0,1]
	v_pk_fma_f32 v[10:11], v[130:131], v[208:209], v[10:11] op_sel_hi:[1,0,1]
	v_add_u32_e32 v27, 0x9900, v48
	ds_read2_b32 v[200:201], v27 offset1:1
	ds_read2_b32 v[202:203], v27 offset0:2 offset1:3
	ds_read2_b32 v[204:205], v27 offset0:4 offset1:5
	ds_read2_b32 v[206:207], v27 offset0:6 offset1:7
	ds_read_b32 v208, v27 offset:32
	s_waitcnt vmcnt(15) lgkmcnt(5)
; __device__ __forceinline__ void ada_phase(LAS unsigned char* lds, const float* c, const float* c_ctx, const float* ada_w, const float* ada_b, float* mods, int G, int bid, int tid, int item0, int item1) {
;     ...
; #pragma unroll 16
;         for (int i = 0; i < 32; ++i) { const int k = ks + 64 * i; const f32x4 w = *(const f32x4*)(wp + (size_t)k * MODW);
; #pragma unroll
;             for (int r = 0; r < 9; ++r) acc[r] += w * sT[k * 9 + r]; }
	v_pk_fma_f32 v[46:47], v[132:133], v[50:51], v[46:47] op_sel_hi:[1,0,1]
	v_pk_fma_f32 v[44:45], v[134:135], v[50:51], v[44:45] op_sel_hi:[1,0,1]
	v_pk_fma_f32 v[42:43], v[132:133], v[50:51], v[42:43] op_sel:[0,1,0]
	v_pk_fma_f32 v[40:41], v[134:135], v[50:51], v[40:41] op_sel:[0,1,0]
	v_pk_fma_f32 v[38:39], v[132:133], v[52:53], v[38:39] op_sel_hi:[1,0,1]
	v_pk_fma_f32 v[36:37], v[134:135], v[52:53], v[36:37] op_sel_hi:[1,0,1]
	v_pk_fma_f32 v[34:35], v[132:133], v[52:53], v[34:35] op_sel:[0,1,0]
	v_pk_fma_f32 v[32:33], v[134:135], v[52:53], v[32:33] op_sel:[0,1,0]
	v_pk_fma_f32 v[30:31], v[132:133], v[54:55], v[30:31] op_sel_hi:[1,0,1]
	v_pk_fma_f32 v[28:29], v[134:135], v[54:55], v[28:29] op_sel_hi:[1,0,1]
	v_pk_fma_f32 v[24:25], v[132:133], v[54:55], v[24:25] op_sel:[0,1,0]
	v_pk_fma_f32 v[22:23], v[134:135], v[54:55], v[22:23] op_sel:[0,1,0]
	v_pk_fma_f32 v[20:21], v[132:133], v[56:57], v[20:21] op_sel_hi:[1,0,1]
	v_pk_fma_f32 v[18:19], v[134:135], v[56:57], v[18:19] op_sel_hi:[1,0,1]
	v_pk_fma_f32 v[16:17], v[132:133], v[56:57], v[16:17] op_sel:[0,1,0]
	v_pk_fma_f32 v[14:15], v[134:135], v[56:57], v[14:15] op_sel:[0,1,0]
	v_pk_fma_f32 v[12:13], v[132:133], v[58:59], v[12:13] op_sel_hi:[1,0,1]
	v_pk_fma_f32 v[10:11], v[134:135], v[58:59], v[10:11] op_sel_hi:[1,0,1]
	v_add_u32_e32 v27, 0xa200, v48
	ds_read2_b32 v[50:51], v27 offset1:1
	ds_read2_b32 v[52:53], v27 offset0:2 offset1:3
	ds_read2_b32 v[54:55], v27 offset0:4 offset1:5
	ds_read2_b32 v[56:57], v27 offset0:6 offset1:7
	ds_read_b32 v58, v27 offset:32
	s_waitcnt vmcnt(14) lgkmcnt(5)
	v_pk_fma_f32 v[46:47], v[136:137], v[200:201], v[46:47] op_sel_hi:[1,0,1]
	v_pk_fma_f32 v[44:45], v[138:139], v[200:201], v[44:45] op_sel_hi:[1,0,1]
	v_pk_fma_f32 v[42:43], v[136:137], v[200:201], v[42:43] op_sel:[0,1,0]
	v_pk_fma_f32 v[40:41], v[138:139], v[200:201], v[40:41] op_sel:[0,1,0]
	v_pk_fma_f32 v[38:39], v[136:137], v[202:203], v[38:39] op_sel_hi:[1,0,1]
	v_pk_fma_f32 v[36:37], v[138:139], v[202:203], v[36:37] op_sel_hi:[1,0,1]
	v_pk_fma_f32 v[34:35], v[136:137], v[202:203], v[34:35] op_sel:[0,1,0]
	v_pk_fma_f32 v[32:33], v[138:139], v[202:203], v[32:33] op_sel:[0,1,0]
	v_pk_fma_f32 v[30:31], v[136:137], v[204:205], v[30:31] op_sel_hi:[1,0,1]
	v_pk_fma_f32 v[28:29], v[138:139], v[204:205], v[28:29] op_sel_hi:[1,0,1]
	v_pk_fma_f32 v[24:25], v[136:137], v[204:205], v[24:25] op_sel:[0,1,0]
	v_pk_fma_f32 v[22:23], v[138:139], v[204:205], v[22:23] op_sel:[0,1,0]
	v_pk_fma_f32 v[20:21], v[136:137], v[206:207], v[20:21] op_sel_hi:[1,0,1]
	v_pk_fma_f32 v[18:19], v[138:139], v[206:207], v[18:19] op_sel_hi:[1,0,1]
	v_pk_fma_f32 v[16:17], v[136:137], v[206:207], v[16:17] op_sel:[0,1,0]
	v_pk_fma_f32 v[14:15], v[138:139], v[206:207], v[14:15] op_sel:[0,1,0]
	v_pk_fma_f32 v[12:13], v[136:137], v[208:209], v[12:13] op_sel_hi:[1,0,1]
	v_pk_fma_f32 v[10:11], v[138:139], v[208:209], v[10:11] op_sel_hi:[1,0,1]
	v_add_u32_e32 v27, 0xab00, v48
	ds_read2_b32 v[200:201], v27 offset1:1
	ds_read2_b32 v[202:203], v27 offset0:2 offset1:3
	ds_read2_b32 v[204:205], v27 offset0:4 offset1:5
	ds_read2_b32 v[206:207], v27 offset0:6 offset1:7
	ds_read_b32 v208, v27 offset:32
	s_waitcnt vmcnt(13) lgkmcnt(5)
	v_pk_fma_f32 v[46:47], v[140:141], v[50:51], v[46:47] op_sel_hi:[1,0,1]
	v_pk_fma_f32 v[44:45], v[142:143], v[50:51], v[44:45] op_sel_hi:[1,0,1]
	v_pk_fma_f32 v[42:43], v[140:141], v[50:51], v[42:43] op_sel:[0,1,0]
	v_pk_fma_f32 v[40:41], v[142:143], v[50:51], v[40:41] op_sel:[0,1,0]
	v_pk_fma_f32 v[38:39], v[140:141], v[52:53], v[38:39] op_sel_hi:[1,0,1]
	v_pk_fma_f32 v[36:37], v[142:143], v[52:53], v[36:37] op_sel_hi:[1,0,1]
	v_pk_fma_f32 v[34:35], v[140:141], v[52:53], v[34:35] op_sel:[0,1,0]
	v_pk_fma_f32 v[32:33], v[142:143], v[52:53], v[32:33] op_sel:[0,1,0]
	v_pk_fma_f32 v[30:31], v[140:141], v[54:55], v[30:31] op_sel_hi:[1,0,1]
	v_pk_fma_f32 v[28:29], v[142:143], v[54:55], v[28:29] op_sel_hi:[1,0,1]
	v_pk_fma_f32 v[24:25], v[140:141], v[54:55], v[24:25] op_sel:[0,1,0]
	v_pk_fma_f32 v[22:23], v[142:143], v[54:55], v[22:23] op_sel:[0,1,0]
	v_pk_fma_f32 v[20:21], v[140:141], v[56:57], v[20:21] op_sel_hi:[1,0,1]
	v_pk_fma_f32 v[18:19], v[142:143], v[56:57], v[18:19] op_sel_hi:[1,0,1]
	v_pk_fma_f32 v[16:17], v[140:141], v[56:57], v[16:17] op_sel:[0,1,0]
	v_pk_fma_f32 v[14:15], v[142:143], v[56:57], v[14:15] op_sel:[0,1,0]
	v_pk_fma_f32 v[12:13], v[140:141], v[58:59], v[12:13] op_sel_hi:[1,0,1]
	v_pk_fma_f32 v[10:11], v[142:143], v[58:59], v[10:11] op_sel_hi:[1,0,1]
	v_add_u32_e32 v27, 0xb400, v48
	ds_read2_b32 v[50:51], v27 offset1:1
	ds_read2_b32 v[52:53], v27 offset0:2 offset1:3
	ds_read2_b32 v[54:55], v27 offset0:4 offset1:5
	ds_read2_b32 v[56:57], v27 offset0:6 offset1:7
	ds_read_b32 v58, v27 offset:32
	s_waitcnt vmcnt(12) lgkmcnt(5)
	v_pk_fma_f32 v[46:47], v[144:145], v[200:201], v[46:47] op_sel_hi:[1,0,1]
	v_pk_fma_f32 v[44:45], v[146:147], v[200:201], v[44:45] op_sel_hi:[1,0,1]
	v_pk_fma_f32 v[42:43], v[144:145], v[200:201], v[42:43] op_sel:[0,1,0]
	v_pk_fma_f32 v[40:41], v[146:147], v[200:201], v[40:41] op_sel:[0,1,0]
	v_pk_fma_f32 v[38:39], v[144:145], v[202:203], v[38:39] op_sel_hi:[1,0,1]
	v_pk_fma_f32 v[36:37], v[146:147], v[202:203], v[36:37] op_sel_hi:[1,0,1]
	v_pk_fma_f32 v[34:35], v[144:145], v[202:203], v[34:35] op_sel:[0,1,0]
	v_pk_fma_f32 v[32:33], v[146:147], v[202:203], v[32:33] op_sel:[0,1,0]
	v_pk_fma_f32 v[30:31], v[144:145], v[204:205], v[30:31] op_sel_hi:[1,0,1]
	v_pk_fma_f32 v[28:29], v[146:147], v[204:205], v[28:29] op_sel_hi:[1,0,1]
	v_pk_fma_f32 v[24:25], v[144:145], v[204:205], v[24:25] op_sel:[0,1,0]
	v_pk_fma_f32 v[22:23], v[146:147], v[204:205], v[22:23] op_sel:[0,1,0]
	v_pk_fma_f32 v[20:21], v[144:145], v[206:207], v[20:21] op_sel_hi:[1,0,1]
	v_pk_fma_f32 v[18:19], v[146:147], v[206:207], v[18:19] op_sel_hi:[1,0,1]
	v_pk_fma_f32 v[16:17], v[144:145], v[206:207], v[16:17] op_sel:[0,1,0]
	v_pk_fma_f32 v[14:15], v[146:147], v[206:207], v[14:15] op_sel:[0,1,0]
	v_pk_fma_f32 v[12:13], v[144:145], v[208:209], v[12:13] op_sel_hi:[1,0,1]
	v_pk_fma_f32 v[10:11], v[146:147], v[208:209], v[10:11] op_sel_hi:[1,0,1]
	v_add_u32_e32 v27, 0xbd00, v48
	ds_read2_b32 v[200:201], v27 offset1:1
	ds_read2_b32 v[202:203], v27 offset0:2 offset1:3
	ds_read2_b32 v[204:205], v27 offset0:4 offset1:5
	ds_read2_b32 v[206:207], v27 offset0:6 offset1:7
	ds_read_b32 v208, v27 offset:32
	s_waitcnt vmcnt(11) lgkmcnt(5)
; __device__ __forceinline__ void ada_phase(LAS unsigned char* lds, const float* c, const float* c_ctx, const float* ada_w, const float* ada_b, float* mods, int G, int bid, int tid, int item0, int item1) {
;     ...
; #pragma unroll 16
;         for (int i = 0; i < 32; ++i) { const int k = ks + 64 * i; const f32x4 w = *(const f32x4*)(wp + (size_t)k * MODW);
; #pragma unroll
;             for (int r = 0; r < 9; ++r) acc[r] += w * sT[k * 9 + r]; }
	v_pk_fma_f32 v[46:47], v[148:149], v[50:51], v[46:47] op_sel_hi:[1,0,1]
	v_pk_fma_f32 v[44:45], v[150:151], v[50:51], v[44:45] op_sel_hi:[1,0,1]
	v_pk_fma_f32 v[42:43], v[148:149], v[50:51], v[42:43] op_sel:[0,1,0]
	v_pk_fma_f32 v[40:41], v[150:151], v[50:51], v[40:41] op_sel:[0,1,0]
	v_pk_fma_f32 v[38:39], v[148:149], v[52:53], v[38:39] op_sel_hi:[1,0,1]
	v_pk_fma_f32 v[36:37], v[150:151], v[52:53], v[36:37] op_sel_hi:[1,0,1]
	v_pk_fma_f32 v[34:35], v[148:149], v[52:53], v[34:35] op_sel:[0,1,0]
	v_pk_fma_f32 v[32:33], v[150:151], v[52:53], v[32:33] op_sel:[0,1,0]
	v_pk_fma_f32 v[30:31], v[148:149], v[54:55], v[30:31] op_sel_hi:[1,0,1]
	v_pk_fma_f32 v[28:29], v[150:151], v[54:55], v[28:29] op_sel_hi:[1,0,1]
	v_pk_fma_f32 v[24:25], v[148:149], v[54:55], v[24:25] op_sel:[0,1,0]
	v_pk_fma_f32 v[22:23], v[150:151], v[54:55], v[22:23] op_sel:[0,1,0]
	v_pk_fma_f32 v[20:21], v[148:149], v[56:57], v[20:21] op_sel_hi:[1,0,1]
	v_pk_fma_f32 v[18:19], v[150:151], v[56:57], v[18:19] op_sel_hi:[1,0,1]
	v_pk_fma_f32 v[16:17], v[148:149], v[56:57], v[16:17] op_sel:[0,1,0]
	v_pk_fma_f32 v[14:15], v[150:151], v[56:57], v[14:15] op_sel:[0,1,0]
	v_pk_fma_f32 v[12:13], v[148:149], v[58:59], v[12:13] op_sel_hi:[1,0,1]
	v_pk_fma_f32 v[10:11], v[150:151], v[58:59], v[10:11] op_sel_hi:[1,0,1]
	v_add_u32_e32 v27, 0xc600, v48
	ds_read2_b32 v[50:51], v27 offset1:1
	ds_read2_b32 v[52:53], v27 offset0:2 offset1:3
	ds_read2_b32 v[54:55], v27 offset0:4 offset1:5
	ds_read2_b32 v[56:57], v27 offset0:6 offset1:7
	ds_read_b32 v58, v27 offset:32
	s_waitcnt vmcnt(10) lgkmcnt(5)
	v_pk_fma_f32 v[46:47], v[152:153], v[200:201], v[46:47] op_sel_hi:[1,0,1]
	v_pk_fma_f32 v[44:45], v[154:155], v[200:201], v[44:45] op_sel_hi:[1,0,1]
	v_pk_fma_f32 v[42:43], v[152:153], v[200:201], v[42:43] op_sel:[0,1,0]
	v_pk_fma_f32 v[40:41], v[154:155], v[200:201], v[40:41] op_sel:[0,1,0]
	v_pk_fma_f32 v[38:39], v[152:153], v[202:203], v[38:39] op_sel_hi:[1,0,1]
	v_pk_fma_f32 v[36:37], v[154:155], v[202:203], v[36:37] op_sel_hi:[1,0,1]
	v_pk_fma_f32 v[34:35], v[152:153], v[202:203], v[34:35] op_sel:[0,1,0]
	v_pk_fma_f32 v[32:33], v[154:155], v[202:203], v[32:33] op_sel:[0,1,0]
	v_pk_fma_f32 v[30:31], v[152:153], v[204:205], v[30:31] op_sel_hi:[1,0,1]
	v_pk_fma_f32 v[28:29], v[154:155], v[204:205], v[28:29] op_sel_hi:[1,0,1]
	v_pk_fma_f32 v[24:25], v[152:153], v[204:205], v[24:25] op_sel:[0,1,0]
	v_pk_fma_f32 v[22:23], v[154:155], v[204:205], v[22:23] op_sel:[0,1,0]
	v_pk_fma_f32 v[20:21], v[152:153], v[206:207], v[20:21] op_sel_hi:[1,0,1]
	v_pk_fma_f32 v[18:19], v[154:155], v[206:207], v[18:19] op_sel_hi:[1,0,1]
	v_pk_fma_f32 v[16:17], v[152:153], v[206:207], v[16:17] op_sel:[0,1,0]
	v_pk_fma_f32 v[14:15], v[154:155], v[206:207], v[14:15] op_sel:[0,1,0]
	v_pk_fma_f32 v[12:13], v[152:153], v[208:209], v[12:13] op_sel_hi:[1,0,1]
	v_pk_fma_f32 v[10:11], v[154:155], v[208:209], v[10:11] op_sel_hi:[1,0,1]
	v_add_u32_e32 v27, 0xcf00, v48
	ds_read2_b32 v[200:201], v27 offset1:1
	ds_read2_b32 v[202:203], v27 offset0:2 offset1:3
	ds_read2_b32 v[204:205], v27 offset0:4 offset1:5
	ds_read2_b32 v[206:207], v27 offset0:6 offset1:7
	ds_read_b32 v208, v27 offset:32
	s_waitcnt vmcnt(9) lgkmcnt(5)
	v_pk_fma_f32 v[46:47], v[156:157], v[50:51], v[46:47] op_sel_hi:[1,0,1]
	v_pk_fma_f32 v[44:45], v[158:159], v[50:51], v[44:45] op_sel_hi:[1,0,1]
	v_pk_fma_f32 v[42:43], v[156:157], v[50:51], v[42:43] op_sel:[0,1,0]
	v_pk_fma_f32 v[40:41], v[158:159], v[50:51], v[40:41] op_sel:[0,1,0]
	v_pk_fma_f32 v[38:39], v[156:157], v[52:53], v[38:39] op_sel_hi:[1,0,1]
	v_pk_fma_f32 v[36:37], v[158:159], v[52:53], v[36:37] op_sel_hi:[1,0,1]
	v_pk_fma_f32 v[34:35], v[156:157], v[52:53], v[34:35] op_sel:[0,1,0]
	v_pk_fma_f32 v[32:33], v[158:159], v[52:53], v[32:33] op_sel:[0,1,0]
	v_pk_fma_f32 v[30:31], v[156:157], v[54:55], v[30:31] op_sel_hi:[1,0,1]
	v_pk_fma_f32 v[28:29], v[158:159], v[54:55], v[28:29] op_sel_hi:[1,0,1]
	v_pk_fma_f32 v[24:25], v[156:157], v[54:55], v[24:25] op_sel:[0,1,0]
	v_pk_fma_f32 v[22:23], v[158:159], v[54:55], v[22:23] op_sel:[0,1,0]
	v_pk_fma_f32 v[20:21], v[156:157], v[56:57], v[20:21] op_sel_hi:[1,0,1]
	v_pk_fma_f32 v[18:19], v[158:159], v[56:57], v[18:19] op_sel_hi:[1,0,1]
	v_pk_fma_f32 v[16:17], v[156:157], v[56:57], v[16:17] op_sel:[0,1,0]
	v_pk_fma_f32 v[14:15], v[158:159], v[56:57], v[14:15] op_sel:[0,1,0]
	v_pk_fma_f32 v[12:13], v[156:157], v[58:59], v[12:13] op_sel_hi:[1,0,1]
	v_pk_fma_f32 v[10:11], v[158:159], v[58:59], v[10:11] op_sel_hi:[1,0,1]
	v_add_u32_e32 v27, 0xd800, v48
	ds_read2_b32 v[50:51], v27 offset1:1
	ds_read2_b32 v[52:53], v27 offset0:2 offset1:3
	ds_read2_b32 v[54:55], v27 offset0:4 offset1:5
	ds_read2_b32 v[56:57], v27 offset0:6 offset1:7
	ds_read_b32 v58, v27 offset:32
	s_waitcnt vmcnt(8) lgkmcnt(5)
	v_pk_fma_f32 v[46:47], v[160:161], v[200:201], v[46:47] op_sel_hi:[1,0,1]
	v_pk_fma_f32 v[44:45], v[162:163], v[200:201], v[44:45] op_sel_hi:[1,0,1]
	v_pk_fma_f32 v[42:43], v[160:161], v[200:201], v[42:43] op_sel:[0,1,0]
	v_pk_fma_f32 v[40:41], v[162:163], v[200:201], v[40:41] op_sel:[0,1,0]
	v_pk_fma_f32 v[38:39], v[160:161], v[202:203], v[38:39] op_sel_hi:[1,0,1]
	v_pk_fma_f32 v[36:37], v[162:163], v[202:203], v[36:37] op_sel_hi:[1,0,1]
	v_pk_fma_f32 v[34:35], v[160:161], v[202:203], v[34:35] op_sel:[0,1,0]
	v_pk_fma_f32 v[32:33], v[162:163], v[202:203], v[32:33] op_sel:[0,1,0]
	v_pk_fma_f32 v[30:31], v[160:161], v[204:205], v[30:31] op_sel_hi:[1,0,1]
	v_pk_fma_f32 v[28:29], v[162:163], v[204:205], v[28:29] op_sel_hi:[1,0,1]
	v_pk_fma_f32 v[24:25], v[160:161], v[204:205], v[24:25] op_sel:[0,1,0]
	v_pk_fma_f32 v[22:23], v[162:163], v[204:205], v[22:23] op_sel:[0,1,0]
	v_pk_fma_f32 v[20:21], v[160:161], v[206:207], v[20:21] op_sel_hi:[1,0,1]
	v_pk_fma_f32 v[18:19], v[162:163], v[206:207], v[18:19] op_sel_hi:[1,0,1]
	v_pk_fma_f32 v[16:17], v[160:161], v[206:207], v[16:17] op_sel:[0,1,0]
	v_pk_fma_f32 v[14:15], v[162:163], v[206:207], v[14:15] op_sel:[0,1,0]
	v_pk_fma_f32 v[12:13], v[160:161], v[208:209], v[12:13] op_sel_hi:[1,0,1]
	v_pk_fma_f32 v[10:11], v[162:163], v[208:209], v[10:11] op_sel_hi:[1,0,1]
	v_add_u32_e32 v27, 0xe100, v48
	ds_read2_b32 v[200:201], v27 offset1:1
	ds_read2_b32 v[202:203], v27 offset0:2 offset1:3
	ds_read2_b32 v[204:205], v27 offset0:4 offset1:5
	ds_read2_b32 v[206:207], v27 offset0:6 offset1:7
	ds_read_b32 v208, v27 offset:32
	s_waitcnt vmcnt(7) lgkmcnt(5)
; __device__ __forceinline__ void ada_phase(LAS unsigned char* lds, const float* c, const float* c_ctx, const float* ada_w, const float* ada_b, float* mods, int G, int bid, int tid, int item0, int item1) {
;     ...
; #pragma unroll 16
;         for (int i = 0; i < 32; ++i) { const int k = ks + 64 * i; const f32x4 w = *(const f32x4*)(wp + (size_t)k * MODW);
; #pragma unroll
;             for (int r = 0; r < 9; ++r) acc[r] += w * sT[k * 9 + r]; }
	v_pk_fma_f32 v[46:47], v[168:169], v[50:51], v[46:47] op_sel_hi:[1,0,1]
	v_pk_fma_f32 v[44:45], v[170:171], v[50:51], v[44:45] op_sel_hi:[1,0,1]
	v_pk_fma_f32 v[42:43], v[168:169], v[50:51], v[42:43] op_sel:[0,1,0]
	v_pk_fma_f32 v[40:41], v[170:171], v[50:51], v[40:41] op_sel:[0,1,0]
	v_pk_fma_f32 v[38:39], v[168:169], v[52:53], v[38:39] op_sel_hi:[1,0,1]
	v_pk_fma_f32 v[36:37], v[170:171], v[52:53], v[36:37] op_sel_hi:[1,0,1]
	v_pk_fma_f32 v[34:35], v[168:169], v[52:53], v[34:35] op_sel:[0,1,0]
	v_pk_fma_f32 v[32:33], v[170:171], v[52:53], v[32:33] op_sel:[0,1,0]
	v_pk_fma_f32 v[30:31], v[168:169], v[54:55], v[30:31] op_sel_hi:[1,0,1]
	v_pk_fma_f32 v[28:29], v[170:171], v[54:55], v[28:29] op_sel_hi:[1,0,1]
	v_pk_fma_f32 v[24:25], v[168:169], v[54:55], v[24:25] op_sel:[0,1,0]
	v_pk_fma_f32 v[22:23], v[170:171], v[54:55], v[22:23] op_sel:[0,1,0]
	v_pk_fma_f32 v[20:21], v[168:169], v[56:57], v[20:21] op_sel_hi:[1,0,1]
	v_pk_fma_f32 v[18:19], v[170:171], v[56:57], v[18:19] op_sel_hi:[1,0,1]
	v_pk_fma_f32 v[16:17], v[168:169], v[56:57], v[16:17] op_sel:[0,1,0]
	v_pk_fma_f32 v[14:15], v[170:171], v[56:57], v[14:15] op_sel:[0,1,0]
	v_pk_fma_f32 v[12:13], v[168:169], v[58:59], v[12:13] op_sel_hi:[1,0,1]
	v_pk_fma_f32 v[10:11], v[170:171], v[58:59], v[10:11] op_sel_hi:[1,0,1]
	v_add_u32_e32 v27, 0xea00, v48
	ds_read2_b32 v[50:51], v27 offset1:1
	ds_read2_b32 v[52:53], v27 offset0:2 offset1:3
	ds_read2_b32 v[54:55], v27 offset0:4 offset1:5
	ds_read2_b32 v[56:57], v27 offset0:6 offset1:7
	ds_read_b32 v58, v27 offset:32
	s_waitcnt vmcnt(6) lgkmcnt(5)
	v_pk_fma_f32 v[46:47], v[172:173], v[200:201], v[46:47] op_sel_hi:[1,0,1]
	v_pk_fma_f32 v[44:45], v[174:175], v[200:201], v[44:45] op_sel_hi:[1,0,1]
	v_pk_fma_f32 v[42:43], v[172:173], v[200:201], v[42:43] op_sel:[0,1,0]
	v_pk_fma_f32 v[40:41], v[174:175], v[200:201], v[40:41] op_sel:[0,1,0]
	v_pk_fma_f32 v[38:39], v[172:173], v[202:203], v[38:39] op_sel_hi:[1,0,1]
	v_pk_fma_f32 v[36:37], v[174:175], v[202:203], v[36:37] op_sel_hi:[1,0,1]
	v_pk_fma_f32 v[34:35], v[172:173], v[202:203], v[34:35] op_sel:[0,1,0]
	v_pk_fma_f32 v[32:33], v[174:175], v[202:203], v[32:33] op_sel:[0,1,0]
	v_pk_fma_f32 v[30:31], v[172:173], v[204:205], v[30:31] op_sel_hi:[1,0,1]
	v_pk_fma_f32 v[28:29], v[174:175], v[204:205], v[28:29] op_sel_hi:[1,0,1]
	v_pk_fma_f32 v[24:25], v[172:173], v[204:205], v[24:25] op_sel:[0,1,0]
	v_pk_fma_f32 v[22:23], v[174:175], v[204:205], v[22:23] op_sel:[0,1,0]
	v_pk_fma_f32 v[20:21], v[172:173], v[206:207], v[20:21] op_sel_hi:[1,0,1]
	v_pk_fma_f32 v[18:19], v[174:175], v[206:207], v[18:19] op_sel_hi:[1,0,1]
	v_pk_fma_f32 v[16:17], v[172:173], v[206:207], v[16:17] op_sel:[0,1,0]
	v_pk_fma_f32 v[14:15], v[174:175], v[206:207], v[14:15] op_sel:[0,1,0]
	v_pk_fma_f32 v[12:13], v[172:173], v[208:209], v[12:13] op_sel_hi:[1,0,1]
	v_pk_fma_f32 v[10:11], v[174:175], v[208:209], v[10:11] op_sel_hi:[1,0,1]
	v_add_u32_e32 v27, 0xf300, v48
	ds_read2_b32 v[200:201], v27 offset1:1
	ds_read2_b32 v[202:203], v27 offset0:2 offset1:3
	ds_read2_b32 v[204:205], v27 offset0:4 offset1:5
	ds_read2_b32 v[206:207], v27 offset0:6 offset1:7
	ds_read_b32 v208, v27 offset:32
	s_waitcnt vmcnt(5) lgkmcnt(5)
	v_pk_fma_f32 v[46:47], v[176:177], v[50:51], v[46:47] op_sel_hi:[1,0,1]
	v_pk_fma_f32 v[44:45], v[178:179], v[50:51], v[44:45] op_sel_hi:[1,0,1]
	v_pk_fma_f32 v[42:43], v[176:177], v[50:51], v[42:43] op_sel:[0,1,0]
	v_pk_fma_f32 v[40:41], v[178:179], v[50:51], v[40:41] op_sel:[0,1,0]
	v_pk_fma_f32 v[38:39], v[176:177], v[52:53], v[38:39] op_sel_hi:[1,0,1]
	v_pk_fma_f32 v[36:37], v[178:179], v[52:53], v[36:37] op_sel_hi:[1,0,1]
	v_pk_fma_f32 v[34:35], v[176:177], v[52:53], v[34:35] op_sel:[0,1,0]
	v_pk_fma_f32 v[32:33], v[178:179], v[52:53], v[32:33] op_sel:[0,1,0]
	v_pk_fma_f32 v[30:31], v[176:177], v[54:55], v[30:31] op_sel_hi:[1,0,1]
	v_pk_fma_f32 v[28:29], v[178:179], v[54:55], v[28:29] op_sel_hi:[1,0,1]
	v_pk_fma_f32 v[24:25], v[176:177], v[54:55], v[24:25] op_sel:[0,1,0]
	v_pk_fma_f32 v[22:23], v[178:179], v[54:55], v[22:23] op_sel:[0,1,0]
	v_pk_fma_f32 v[20:21], v[176:177], v[56:57], v[20:21] op_sel_hi:[1,0,1]
	v_pk_fma_f32 v[18:19], v[178:179], v[56:57], v[18:19] op_sel_hi:[1,0,1]
	v_pk_fma_f32 v[16:17], v[176:177], v[56:57], v[16:17] op_sel:[0,1,0]
	v_pk_fma_f32 v[14:15], v[178:179], v[56:57], v[14:15] op_sel:[0,1,0]
	v_pk_fma_f32 v[12:13], v[176:177], v[58:59], v[12:13] op_sel_hi:[1,0,1]
	v_pk_fma_f32 v[10:11], v[178:179], v[58:59], v[10:11] op_sel_hi:[1,0,1]
	v_add_u32_e32 v27, 0xfc00, v48
	ds_read2_b32 v[50:51], v27 offset1:1
	ds_read2_b32 v[52:53], v27 offset0:2 offset1:3
	ds_read2_b32 v[54:55], v27 offset0:4 offset1:5
	ds_read2_b32 v[56:57], v27 offset0:6 offset1:7
	ds_read_b32 v58, v27 offset:32
	s_waitcnt vmcnt(4) lgkmcnt(5)
	v_pk_fma_f32 v[46:47], v[180:181], v[200:201], v[46:47] op_sel_hi:[1,0,1]
	v_pk_fma_f32 v[44:45], v[182:183], v[200:201], v[44:45] op_sel_hi:[1,0,1]
	v_pk_fma_f32 v[42:43], v[180:181], v[200:201], v[42:43] op_sel:[0,1,0]
	v_pk_fma_f32 v[40:41], v[182:183], v[200:201], v[40:41] op_sel:[0,1,0]
	v_pk_fma_f32 v[38:39], v[180:181], v[202:203], v[38:39] op_sel_hi:[1,0,1]
	v_pk_fma_f32 v[36:37], v[182:183], v[202:203], v[36:37] op_sel_hi:[1,0,1]
	v_pk_fma_f32 v[34:35], v[180:181], v[202:203], v[34:35] op_sel:[0,1,0]
	v_pk_fma_f32 v[32:33], v[182:183], v[202:203], v[32:33] op_sel:[0,1,0]
	v_pk_fma_f32 v[30:31], v[180:181], v[204:205], v[30:31] op_sel_hi:[1,0,1]
	v_pk_fma_f32 v[28:29], v[182:183], v[204:205], v[28:29] op_sel_hi:[1,0,1]
	v_pk_fma_f32 v[24:25], v[180:181], v[204:205], v[24:25] op_sel:[0,1,0]
	v_pk_fma_f32 v[22:23], v[182:183], v[204:205], v[22:23] op_sel:[0,1,0]
	v_pk_fma_f32 v[20:21], v[180:181], v[206:207], v[20:21] op_sel_hi:[1,0,1]
	v_pk_fma_f32 v[18:19], v[182:183], v[206:207], v[18:19] op_sel_hi:[1,0,1]
	v_pk_fma_f32 v[16:17], v[180:181], v[206:207], v[16:17] op_sel:[0,1,0]
	v_pk_fma_f32 v[14:15], v[182:183], v[206:207], v[14:15] op_sel:[0,1,0]
	v_pk_fma_f32 v[12:13], v[180:181], v[208:209], v[12:13] op_sel_hi:[1,0,1]
	v_pk_fma_f32 v[10:11], v[182:183], v[208:209], v[10:11] op_sel_hi:[1,0,1]
	v_add_u32_e32 v27, 0x10500, v48
	ds_read2_b32 v[200:201], v27 offset1:1
	ds_read2_b32 v[202:203], v27 offset0:2 offset1:3
	ds_read2_b32 v[204:205], v27 offset0:4 offset1:5
	ds_read2_b32 v[206:207], v27 offset0:6 offset1:7
	ds_read_b32 v208, v27 offset:32
	s_waitcnt vmcnt(3) lgkmcnt(5)
; __device__ __forceinline__ void ada_phase(LAS unsigned char* lds, const float* c, const float* c_ctx, const float* ada_w, const float* ada_b, float* mods, int G, int bid, int tid, int item0, int item1) {
;     ...
; #pragma unroll 16
;         for (int i = 0; i < 32; ++i) { const int k = ks + 64 * i; const f32x4 w = *(const f32x4*)(wp + (size_t)k * MODW);
; #pragma unroll
;             for (int r = 0; r < 9; ++r) acc[r] += w * sT[k * 9 + r]; }
; #pragma unroll
;         for (int r = 0; r < 9; ++r)
; #pragma unroll
;             for (int e = 0; e < 4; ++e) { float v = acc[r][e]; v += __shfl_xor(v, 8); v += __shfl_xor(v, 16); v += __shfl_xor(v, 32); acc[r][e] = v; }
	v_pk_fma_f32 v[46:47], v[184:185], v[50:51], v[46:47] op_sel_hi:[1,0,1]
	v_pk_fma_f32 v[44:45], v[186:187], v[50:51], v[44:45] op_sel_hi:[1,0,1]
	v_pk_fma_f32 v[42:43], v[184:185], v[50:51], v[42:43] op_sel:[0,1,0]
	v_pk_fma_f32 v[40:41], v[186:187], v[50:51], v[40:41] op_sel:[0,1,0]
	v_pk_fma_f32 v[38:39], v[184:185], v[52:53], v[38:39] op_sel_hi:[1,0,1]
	v_pk_fma_f32 v[36:37], v[186:187], v[52:53], v[36:37] op_sel_hi:[1,0,1]
	v_pk_fma_f32 v[34:35], v[184:185], v[52:53], v[34:35] op_sel:[0,1,0]
	v_pk_fma_f32 v[32:33], v[186:187], v[52:53], v[32:33] op_sel:[0,1,0]
	v_pk_fma_f32 v[30:31], v[184:185], v[54:55], v[30:31] op_sel_hi:[1,0,1]
	v_pk_fma_f32 v[28:29], v[186:187], v[54:55], v[28:29] op_sel_hi:[1,0,1]
	v_pk_fma_f32 v[24:25], v[184:185], v[54:55], v[24:25] op_sel:[0,1,0]
	v_pk_fma_f32 v[22:23], v[186:187], v[54:55], v[22:23] op_sel:[0,1,0]
	v_pk_fma_f32 v[20:21], v[184:185], v[56:57], v[20:21] op_sel_hi:[1,0,1]
	v_pk_fma_f32 v[18:19], v[186:187], v[56:57], v[18:19] op_sel_hi:[1,0,1]
	v_pk_fma_f32 v[16:17], v[184:185], v[56:57], v[16:17] op_sel:[0,1,0]
	v_pk_fma_f32 v[14:15], v[186:187], v[56:57], v[14:15] op_sel:[0,1,0]
	v_pk_fma_f32 v[12:13], v[184:185], v[58:59], v[12:13] op_sel_hi:[1,0,1]
	v_pk_fma_f32 v[10:11], v[186:187], v[58:59], v[10:11] op_sel_hi:[1,0,1]
	v_add_u32_e32 v27, 0x10e00, v48
	ds_read2_b32 v[50:51], v27 offset1:1
	ds_read2_b32 v[52:53], v27 offset0:2 offset1:3
	ds_read2_b32 v[54:55], v27 offset0:4 offset1:5
	ds_read2_b32 v[56:57], v27 offset0:6 offset1:7
	ds_read_b32 v58, v27 offset:32
	s_waitcnt vmcnt(2) lgkmcnt(5)
	v_pk_fma_f32 v[46:47], v[188:189], v[200:201], v[46:47] op_sel_hi:[1,0,1]
	v_pk_fma_f32 v[44:45], v[190:191], v[200:201], v[44:45] op_sel_hi:[1,0,1]
	v_pk_fma_f32 v[42:43], v[188:189], v[200:201], v[42:43] op_sel:[0,1,0]
	v_pk_fma_f32 v[40:41], v[190:191], v[200:201], v[40:41] op_sel:[0,1,0]
	v_pk_fma_f32 v[38:39], v[188:189], v[202:203], v[38:39] op_sel_hi:[1,0,1]
	v_pk_fma_f32 v[36:37], v[190:191], v[202:203], v[36:37] op_sel_hi:[1,0,1]
	v_pk_fma_f32 v[34:35], v[188:189], v[202:203], v[34:35] op_sel:[0,1,0]
	v_pk_fma_f32 v[32:33], v[190:191], v[202:203], v[32:33] op_sel:[0,1,0]
	v_pk_fma_f32 v[30:31], v[188:189], v[204:205], v[30:31] op_sel_hi:[1,0,1]
	v_pk_fma_f32 v[28:29], v[190:191], v[204:205], v[28:29] op_sel_hi:[1,0,1]
	v_pk_fma_f32 v[24:25], v[188:189], v[204:205], v[24:25] op_sel:[0,1,0]
	v_pk_fma_f32 v[22:23], v[190:191], v[204:205], v[22:23] op_sel:[0,1,0]
	v_pk_fma_f32 v[20:21], v[188:189], v[206:207], v[20:21] op_sel_hi:[1,0,1]
	v_pk_fma_f32 v[18:19], v[190:191], v[206:207], v[18:19] op_sel_hi:[1,0,1]
	v_pk_fma_f32 v[16:17], v[188:189], v[206:207], v[16:17] op_sel:[0,1,0]
	v_pk_fma_f32 v[14:15], v[190:191], v[206:207], v[14:15] op_sel:[0,1,0]
	v_pk_fma_f32 v[12:13], v[188:189], v[208:209], v[12:13] op_sel_hi:[1,0,1]
	v_pk_fma_f32 v[10:11], v[190:191], v[208:209], v[10:11] op_sel_hi:[1,0,1]
	v_add_u32_e32 v27, 0x11700, v48
	ds_read2_b32 v[200:201], v27 offset1:1
	ds_read2_b32 v[202:203], v27 offset0:2 offset1:3
	ds_read2_b32 v[204:205], v27 offset0:4 offset1:5
	ds_read2_b32 v[206:207], v27 offset0:6 offset1:7
	ds_read_b32 v208, v27 offset:32
	s_waitcnt vmcnt(1) lgkmcnt(5)
	v_pk_fma_f32 v[46:47], v[192:193], v[50:51], v[46:47] op_sel_hi:[1,0,1]
	v_pk_fma_f32 v[44:45], v[194:195], v[50:51], v[44:45] op_sel_hi:[1,0,1]
	v_pk_fma_f32 v[42:43], v[192:193], v[50:51], v[42:43] op_sel:[0,1,0]
	v_pk_fma_f32 v[40:41], v[194:195], v[50:51], v[40:41] op_sel:[0,1,0]
	v_pk_fma_f32 v[38:39], v[192:193], v[52:53], v[38:39] op_sel_hi:[1,0,1]
	v_pk_fma_f32 v[36:37], v[194:195], v[52:53], v[36:37] op_sel_hi:[1,0,1]
	v_pk_fma_f32 v[34:35], v[192:193], v[52:53], v[34:35] op_sel:[0,1,0]
	v_pk_fma_f32 v[32:33], v[194:195], v[52:53], v[32:33] op_sel:[0,1,0]
	v_pk_fma_f32 v[30:31], v[192:193], v[54:55], v[30:31] op_sel_hi:[1,0,1]
	v_pk_fma_f32 v[28:29], v[194:195], v[54:55], v[28:29] op_sel_hi:[1,0,1]
	v_pk_fma_f32 v[24:25], v[192:193], v[54:55], v[24:25] op_sel:[0,1,0]
	v_pk_fma_f32 v[22:23], v[194:195], v[54:55], v[22:23] op_sel:[0,1,0]
	v_pk_fma_f32 v[20:21], v[192:193], v[56:57], v[20:21] op_sel_hi:[1,0,1]
	v_pk_fma_f32 v[18:19], v[194:195], v[56:57], v[18:19] op_sel_hi:[1,0,1]
	v_pk_fma_f32 v[16:17], v[192:193], v[56:57], v[16:17] op_sel:[0,1,0]
	v_pk_fma_f32 v[14:15], v[194:195], v[56:57], v[14:15] op_sel:[0,1,0]
	v_pk_fma_f32 v[12:13], v[192:193], v[58:59], v[12:13] op_sel_hi:[1,0,1]
	v_pk_fma_f32 v[10:11], v[194:195], v[58:59], v[10:11] op_sel_hi:[1,0,1]
	s_waitcnt vmcnt(0) lgkmcnt(0)
	v_pk_fma_f32 v[46:47], v[196:197], v[200:201], v[46:47] op_sel_hi:[1,0,1]
	v_pk_fma_f32 v[44:45], v[198:199], v[200:201], v[44:45] op_sel_hi:[1,0,1]
	v_pk_fma_f32 v[42:43], v[196:197], v[200:201], v[42:43] op_sel:[0,1,0]
	v_pk_fma_f32 v[40:41], v[198:199], v[200:201], v[40:41] op_sel:[0,1,0]
	v_pk_fma_f32 v[38:39], v[196:197], v[202:203], v[38:39] op_sel_hi:[1,0,1]
	v_pk_fma_f32 v[36:37], v[198:199], v[202:203], v[36:37] op_sel_hi:[1,0,1]
	v_pk_fma_f32 v[34:35], v[196:197], v[202:203], v[34:35] op_sel:[0,1,0]
	v_pk_fma_f32 v[32:33], v[198:199], v[202:203], v[32:33] op_sel:[0,1,0]
	v_pk_fma_f32 v[30:31], v[196:197], v[204:205], v[30:31] op_sel_hi:[1,0,1]
	v_pk_fma_f32 v[28:29], v[198:199], v[204:205], v[28:29] op_sel_hi:[1,0,1]
	v_pk_fma_f32 v[24:25], v[196:197], v[204:205], v[24:25] op_sel:[0,1,0]
	v_pk_fma_f32 v[22:23], v[198:199], v[204:205], v[22:23] op_sel:[0,1,0]
	v_pk_fma_f32 v[20:21], v[196:197], v[206:207], v[20:21] op_sel_hi:[1,0,1]
	v_pk_fma_f32 v[18:19], v[198:199], v[206:207], v[18:19] op_sel_hi:[1,0,1]
	v_pk_fma_f32 v[16:17], v[196:197], v[206:207], v[16:17] op_sel:[0,1,0]
	v_pk_fma_f32 v[14:15], v[198:199], v[206:207], v[14:15] op_sel:[0,1,0]
	v_pk_fma_f32 v[12:13], v[196:197], v[208:209], v[12:13] op_sel_hi:[1,0,1]
	v_pk_fma_f32 v[10:11], v[198:199], v[208:209], v[10:11] op_sel_hi:[1,0,1]
	ds_bpermute_b32 v56, v3, v34
	ds_bpermute_b32 v57, v3, v35
	ds_bpermute_b32 v58, v3, v32
	ds_bpermute_b32 v59, v3, v33
	ds_bpermute_b32 v26, v3, v44
	ds_bpermute_b32 v27, v3, v45
	s_waitcnt lgkmcnt(4)
; __device__ __forceinline__ void ada_phase(LAS unsigned char* lds, const float* c, const float* c_ctx, const float* ada_w, const float* ada_b, float* mods, int G, int bid, int tid, int item0, int item1) {
;     ...
; #pragma unroll
;         for (int r = 0; r < 9; ++r)
; #pragma unroll
;             for (int e = 0; e < 4; ++e) { float v = acc[r][e]; v += __shfl_xor(v, 8); v += __shfl_xor(v, 16); v += __shfl_xor(v, 32); acc[r][e] = v; }
;         if (lane < 8) {
; #pragma unroll
;             for (int r = 0; r < 9; ++r)
; #pragma unroll
;                 for (int e = 0; e < 4; ++e) red[(wave * 9 + r) * 32 + 4 * cgp + e] = acc[r][e];
;         }
	v_pk_add_f32 v[34:35], v[34:35], v[56:57]
	ds_bpermute_b32 v56, v80, v34
	s_waitcnt lgkmcnt(3)
	v_pk_add_f32 v[58:59], v[32:33], v[58:59]
	ds_bpermute_b32 v57, v80, v35
	ds_bpermute_b32 v60, v80, v58
	ds_bpermute_b32 v61, v80, v59
	ds_bpermute_b32 v62, v3, v28
	ds_bpermute_b32 v63, v3, v29
	s_waitcnt lgkmcnt(4)
	v_pk_add_f32 v[32:33], v[34:35], v[56:57]
	v_pk_add_f32 v[44:45], v[44:45], v[26:27]
	s_waitcnt lgkmcnt(2)
	v_pk_add_f32 v[56:57], v[58:59], v[60:61]
	ds_bpermute_b32 v60, v3, v30
	ds_bpermute_b32 v61, v3, v31
	ds_bpermute_b32 v52, v3, v38
	ds_bpermute_b32 v53, v3, v39
	s_waitcnt lgkmcnt(4)
	v_pk_add_f32 v[62:63], v[28:29], v[62:63]
	ds_bpermute_b32 v72, v3, v16
	s_waitcnt lgkmcnt(3)
	v_pk_add_f32 v[30:31], v[30:31], v[60:61]
	ds_bpermute_b32 v73, v3, v17
	ds_bpermute_b32 v50, v80, v44
	ds_bpermute_b32 v51, v80, v45
	ds_bpermute_b32 v60, v80, v30
	ds_bpermute_b32 v61, v80, v31
	ds_bpermute_b32 v64, v80, v62
	ds_bpermute_b32 v65, v80, v63
	ds_bpermute_b32 v66, v3, v24
	ds_bpermute_b32 v67, v3, v25
	s_waitcnt lgkmcnt(10)
	v_pk_add_f32 v[38:39], v[38:39], v[52:53]
	s_waitcnt lgkmcnt(8)
	v_pk_add_f32 v[16:17], v[16:17], v[72:73]
	ds_bpermute_b32 v8, v3, v46
	ds_bpermute_b32 v9, v3, v47
	ds_bpermute_b32 v48, v3, v42
	ds_bpermute_b32 v49, v3, v43
	s_waitcnt lgkmcnt(10)
	v_pk_add_f32 v[44:45], v[44:45], v[50:51]
	ds_bpermute_b32 v50, v3, v40
	ds_bpermute_b32 v51, v3, v41
	ds_bpermute_b32 v52, v80, v38
	ds_bpermute_b32 v53, v80, v39
	ds_bpermute_b32 v54, v3, v36
	ds_bpermute_b32 v55, v3, v37
	s_waitcnt lgkmcnt(14)
	v_pk_add_f32 v[28:29], v[30:31], v[60:61]
	s_waitcnt lgkmcnt(12)
	v_pk_add_f32 v[60:61], v[62:63], v[64:65]
	s_waitcnt lgkmcnt(10)
	v_pk_add_f32 v[62:63], v[24:25], v[66:67]
	ds_bpermute_b32 v66, v3, v22
	ds_bpermute_b32 v67, v3, v23
	ds_bpermute_b32 v68, v3, v20
	ds_bpermute_b32 v69, v3, v21
	ds_bpermute_b32 v70, v3, v18
	ds_bpermute_b32 v71, v3, v19
	ds_bpermute_b32 v72, v80, v16
	ds_bpermute_b32 v73, v80, v17
	ds_bpermute_b32 v74, v3, v14
	ds_bpermute_b32 v75, v3, v15
	ds_bpermute_b32 v76, v3, v12
	ds_bpermute_b32 v77, v3, v13
	ds_bpermute_b32 v78, v3, v10
	ds_bpermute_b32 v79, v3, v11
	s_waitcnt lgkmcnt(14)
	v_pk_add_f32 v[8:9], v[46:47], v[8:9]
	v_pk_add_f32 v[42:43], v[42:43], v[48:49]
	v_pk_add_f32 v[40:41], v[40:41], v[50:51]
	v_pk_add_f32 v[38:39], v[38:39], v[52:53]
	v_pk_add_f32 v[52:53], v[36:37], v[54:55]
	s_waitcnt lgkmcnt(12)
	v_pk_add_f32 v[22:23], v[22:23], v[66:67]
	s_waitcnt lgkmcnt(10)
	v_pk_add_f32 v[20:21], v[20:21], v[68:69]
	s_waitcnt lgkmcnt(8)
	v_pk_add_f32 v[18:19], v[18:19], v[70:71]
	s_waitcnt lgkmcnt(6)
	v_pk_add_f32 v[16:17], v[16:17], v[72:73]
	s_waitcnt lgkmcnt(4)
	v_pk_add_f32 v[72:73], v[14:15], v[74:75]
	s_waitcnt lgkmcnt(2)
	v_pk_add_f32 v[12:13], v[12:13], v[76:77]
	s_waitcnt lgkmcnt(0)
	v_pk_add_f32 v[78:79], v[10:11], v[78:79]
	ds_bpermute_b32 v46, v80, v8
	ds_bpermute_b32 v47, v80, v9
	ds_bpermute_b32 v48, v80, v42
	ds_bpermute_b32 v49, v80, v43
	ds_bpermute_b32 v50, v80, v40
	ds_bpermute_b32 v51, v80, v41
	ds_bpermute_b32 v54, v80, v52
	ds_bpermute_b32 v55, v80, v53
	ds_bpermute_b32 v64, v80, v62
	ds_bpermute_b32 v65, v80, v63
	ds_bpermute_b32 v66, v80, v22
	ds_bpermute_b32 v67, v80, v23
	ds_bpermute_b32 v68, v80, v20
	ds_bpermute_b32 v69, v80, v21
	ds_bpermute_b32 v70, v80, v18
	ds_bpermute_b32 v71, v80, v19
	ds_bpermute_b32 v74, v80, v72
	ds_bpermute_b32 v75, v80, v73
	ds_bpermute_b32 v76, v80, v12
	ds_bpermute_b32 v77, v80, v13
	ds_bpermute_b32 v84, v80, v78
	ds_bpermute_b32 v85, v80, v79
	s_waitcnt lgkmcnt(14)
	v_pk_add_f32 v[8:9], v[8:9], v[46:47]
	v_pk_add_f32 v[42:43], v[42:43], v[48:49]
	v_pk_add_f32 v[40:41], v[40:41], v[50:51]
	v_pk_add_f32 v[52:53], v[52:53], v[54:55]
	s_waitcnt lgkmcnt(12)
	v_pk_add_f32 v[62:63], v[62:63], v[64:65]
	s_waitcnt lgkmcnt(10)
	v_pk_add_f32 v[22:23], v[22:23], v[66:67]
	s_waitcnt lgkmcnt(8)
	v_pk_add_f32 v[20:21], v[20:21], v[68:69]
	s_waitcnt lgkmcnt(6)
	v_pk_add_f32 v[18:19], v[18:19], v[70:71]
	s_waitcnt lgkmcnt(4)
	v_pk_add_f32 v[72:73], v[72:73], v[74:75]
	s_waitcnt lgkmcnt(2)
	v_pk_add_f32 v[10:11], v[12:13], v[76:77]
	s_waitcnt lgkmcnt(0)
	v_pk_add_f32 v[76:77], v[78:79], v[84:85]
	ds_bpermute_b32 v26, v81, v8
	ds_bpermute_b32 v27, v81, v9
	ds_bpermute_b32 v46, v81, v44
	ds_bpermute_b32 v47, v81, v45
	ds_bpermute_b32 v48, v81, v42
	ds_bpermute_b32 v49, v81, v43
	ds_bpermute_b32 v50, v81, v40
	ds_bpermute_b32 v51, v81, v41
	ds_bpermute_b32 v36, v81, v38
	ds_bpermute_b32 v37, v81, v39
	ds_bpermute_b32 v54, v81, v52
	ds_bpermute_b32 v55, v81, v53
	ds_bpermute_b32 v34, v81, v32
	ds_bpermute_b32 v35, v81, v33
	ds_bpermute_b32 v58, v81, v56
	ds_bpermute_b32 v59, v81, v57
	ds_bpermute_b32 v30, v81, v28
	ds_bpermute_b32 v31, v81, v29
	ds_bpermute_b32 v24, v81, v60
	ds_bpermute_b32 v25, v81, v61
	ds_bpermute_b32 v64, v81, v62
	ds_bpermute_b32 v65, v81, v63
	ds_bpermute_b32 v66, v81, v22
	ds_bpermute_b32 v67, v81, v23
	ds_bpermute_b32 v68, v81, v20
	ds_bpermute_b32 v69, v81, v21
	ds_bpermute_b32 v70, v81, v18
	ds_bpermute_b32 v71, v81, v19
	ds_bpermute_b32 v14, v81, v16
	ds_bpermute_b32 v15, v81, v17
	ds_bpermute_b32 v74, v81, v72
	ds_bpermute_b32 v75, v81, v73
	ds_bpermute_b32 v12, v81, v10
	ds_bpermute_b32 v13, v81, v11
	ds_bpermute_b32 v78, v81, v76
	ds_bpermute_b32 v79, v81, v77
	s_and_saveexec_b64 s[8:9], vcc
	s_cbranch_execz .LBB0_386
	s_waitcnt lgkmcnt(14)
	v_pk_add_f32 v[84:85], v[8:9], v[26:27]
	v_pk_add_f32 v[26:27], v[28:29], v[30:31]
	v_pk_add_f32 v[28:29], v[60:61], v[24:25]
	v_pk_add_f32 v[86:87], v[44:45], v[46:47]
	v_pk_add_f32 v[42:43], v[42:43], v[48:49]
	v_pk_add_f32 v[44:45], v[40:41], v[50:51]
	v_pk_add_f32 v[36:37], v[38:39], v[36:37]
	v_pk_add_f32 v[38:39], v[52:53], v[54:55]
	v_pk_add_f32 v[32:33], v[32:33], v[34:35]
	v_pk_add_f32 v[34:35], v[56:57], v[58:59]
	ds_write_b128 v5, v[26:29] offset:512
	v_pk_add_f32 v[24:25], v[62:63], v[64:65]
	s_waitcnt lgkmcnt(13)
	v_pk_add_f32 v[26:27], v[22:23], v[66:67]
	s_waitcnt lgkmcnt(11)
	v_pk_add_f32 v[20:21], v[20:21], v[68:69]
	s_waitcnt lgkmcnt(9)
	v_pk_add_f32 v[22:23], v[18:19], v[70:71]
	s_waitcnt lgkmcnt(7)
	v_pk_add_f32 v[14:15], v[16:17], v[14:15]
	s_waitcnt lgkmcnt(5)
	v_pk_add_f32 v[16:17], v[72:73], v[74:75]
	s_waitcnt lgkmcnt(3)
	v_pk_add_f32 v[8:9], v[10:11], v[12:13]
	s_waitcnt lgkmcnt(1)
	v_pk_add_f32 v[10:11], v[76:77], v[78:79]
	ds_write_b128 v5, v[84:87]
	ds_write_b128 v5, v[42:45] offset:128
	ds_write_b128 v5, v[36:39] offset:256
	ds_write_b128 v5, v[32:35] offset:384
	ds_write_b128 v5, v[24:27] offset:640
	ds_write_b128 v5, v[20:23] offset:768
	ds_write_b128 v5, v[14:17] offset:896
	ds_write_b128 v5, v[8:11] offset:1024

; __device__ __forceinline__ void t_load(float (&v)[32], const float* W, int K, int N, int item, int lane) {
;     const int nkb = K / 64, grp = item >> 3, w8 = item & 7, kb = 2 * (grp % (nkb / 2)) + (w8 & 1), nb = 4 * (grp / (nkb / 2)) + (w8 >> 1);
;     const float* p = W + (size_t)(64 * kb + (lane >> 5)) * N + 32 * nb + (lane & 31);
; #pragma unroll
;     for (int i = 0; i < 32; ++i) v[i] = p[(size_t)(2 * i) * N];
; __global__ void __launch_bounds__(NTHR, 2) mega_fwd(Args args) {
;     ...
;                     if (it < i1) { P0_DECODE(it, aW, aK, aN, aWT, amode, ar); t_load(A, aW, aK, aN, ar, lane); }
;                     if (it + hstep < i1) { P0_DECODE(it + hstep, bW, bK, bN, bWT, bmode, br); t_load(B, bW, bK, bN, br, lane); }
.LBB0_430:
	s_lshr_b32 s18, s38, 7
	v_cvt_f32_u32_e32 v1, s18
	s_sub_i32 s21, 0, s18
	s_ashr_i32 s17, s40, 3
	s_abs_i32 s19, s17
	v_rcp_iflag_f32_e32 v1, v1
	s_ashr_i32 s16, s40, 31
	v_lshlrev_b32_e32 v4, 2, v96
	v_mov_b32_e32 v5, v0
	v_mul_f32_e32 v1, 0x4f7ffffe, v1
	v_cvt_u32_f32_e32 v1, v1
	s_nop 0
	v_readfirstlane_b32 s22, v1
	s_mul_i32 s21, s21, s22
	s_mul_hi_u32 s21, s22, s21
	s_add_i32 s22, s22, s21
	s_mul_hi_u32 s21, s19, s22
	s_mul_i32 s22, s21, s18
	s_sub_i32 s19, s19, s22
	s_add_i32 s22, s21, 1
	s_sub_i32 s23, s19, s18
	s_cmp_ge_u32 s19, s18
	s_cselect_b32 s21, s22, s21
	s_cselect_b32 s19, s23, s19
	s_add_i32 s22, s21, 1
	s_cmp_ge_u32 s19, s18
	s_cselect_b32 s19, s22, s21
	s_xor_b32 s19, s19, s16
	s_sub_i32 s16, s19, s16
	s_mul_i32 s18, s16, s18
	s_sub_i32 s17, s17, s18
	s_lshl_b32 s18, s40, 6
	s_lshl_b32 s17, s17, 7
	s_and_b32 s18, s18, 64
	s_or_b32 s18, s17, s18
	v_lshrrev_b32_e32 v1, 5, v97
	v_or_b32_e32 v1, s18, v1
	s_ashr_i32 s17, s17, 31
	s_mul_i32 s17, s17, s2
	v_mad_u64_u32 v[2:3], s[18:19], v1, s2, 0
	v_add_u32_e32 v3, s17, v3
	s_waitcnt lgkmcnt(0)
	v_lshl_add_u64 v[2:3], v[2:3], 2, s[10:11]
	s_lshl_b32 s11, s40, 4
	s_lshl_b32 s10, s16, 7
	s_and_b32 s11, s11, 0x60
	s_or_b32 s10, s10, s11
	s_ashr_i32 s11, s10, 31
	v_lshl_add_u64 v[2:3], s[10:11], 2, v[2:3]
	v_lshl_add_u64 v[2:3], v[2:3], 0, v[4:5]
	s_lshl_b32 s90, s2, 1
	v_lshl_add_u64 v[4:5], s[90:91], 2, v[2:3]
	s_lshl_b32 s90, s2, 2
	global_load_dword v32, v[2:3], off nt
	global_load_dword v33, v[4:5], off nt
	v_lshl_add_u64 v[4:5], s[90:91], 2, v[2:3]
	s_mul_i32 s90, s2, 6
	global_load_dword v34, v[4:5], off nt
	v_lshl_add_u64 v[4:5], s[90:91], 2, v[2:3]
	s_lshl_b32 s90, s2, 3
	global_load_dword v35, v[4:5], off nt
	v_lshl_add_u64 v[4:5], s[90:91], 2, v[2:3]
	s_mul_i32 s90, s2, 10
	global_load_dword v36, v[4:5], off nt
	v_lshl_add_u64 v[4:5], s[90:91], 2, v[2:3]
	s_mul_i32 s90, s2, 12
	global_load_dword v37, v[4:5], off nt
	v_lshl_add_u64 v[4:5], s[90:91], 2, v[2:3]
	s_mul_i32 s90, s2, 14
	global_load_dword v38, v[4:5], off nt
	v_lshl_add_u64 v[4:5], s[90:91], 2, v[2:3]
	s_lshl_b32 s90, s2, 4
	global_load_dword v39, v[4:5], off nt
	v_lshl_add_u64 v[4:5], s[90:91], 2, v[2:3]
	s_mul_i32 s90, s2, 18
	global_load_dword v40, v[4:5], off nt
	v_lshl_add_u64 v[4:5], s[90:91], 2, v[2:3]
	s_mul_i32 s90, s2, 20
	global_load_dword v41, v[4:5], off nt
	v_lshl_add_u64 v[4:5], s[90:91], 2, v[2:3]
	s_mul_i32 s90, s2, 22
	global_load_dword v42, v[4:5], off nt
	v_lshl_add_u64 v[4:5], s[90:91], 2, v[2:3]
	s_mul_i32 s90, s2, 24
	global_load_dword v43, v[4:5], off nt
	v_lshl_add_u64 v[4:5], s[90:91], 2, v[2:3]
	s_mul_i32 s90, s2, 26
	global_load_dword v44, v[4:5], off nt
	v_lshl_add_u64 v[4:5], s[90:91], 2, v[2:3]
	s_mul_i32 s90, s2, 28
	global_load_dword v45, v[4:5], off nt
	v_lshl_add_u64 v[4:5], s[90:91], 2, v[2:3]
	s_mul_i32 s90, s2, 30
	global_load_dword v46, v[4:5], off nt
	v_lshl_add_u64 v[4:5], s[90:91], 2, v[2:3]
	s_lshl_b32 s90, s2, 5
	global_load_dword v47, v[4:5], off nt
	v_lshl_add_u64 v[4:5], s[90:91], 2, v[2:3]
	s_mul_i32 s90, s2, 34
	global_load_dword v48, v[4:5], off nt
	v_lshl_add_u64 v[4:5], s[90:91], 2, v[2:3]
	s_mul_i32 s90, s2, 36
	global_load_dword v49, v[4:5], off nt
	v_lshl_add_u64 v[4:5], s[90:91], 2, v[2:3]
	s_mul_i32 s90, s2, 38
	global_load_dword v50, v[4:5], off nt
	v_lshl_add_u64 v[4:5], s[90:91], 2, v[2:3]
	s_mul_i32 s90, s2, 40
	global_load_dword v51, v[4:5], off nt
	v_lshl_add_u64 v[4:5], s[90:91], 2, v[2:3]
	s_mul_i32 s90, s2, 42
	global_load_dword v52, v[4:5], off nt
	v_lshl_add_u64 v[4:5], s[90:91], 2, v[2:3]
	s_mul_i32 s90, s2, 44
	global_load_dword v53, v[4:5], off nt
	v_lshl_add_u64 v[4:5], s[90:91], 2, v[2:3]
	s_mul_i32 s90, s2, 46
	global_load_dword v54, v[4:5], off nt
	v_lshl_add_u64 v[4:5], s[90:91], 2, v[2:3]
	s_mul_i32 s90, s2, 48
	global_load_dword v55, v[4:5], off nt
	v_lshl_add_u64 v[4:5], s[90:91], 2, v[2:3]
	s_mul_i32 s90, s2, 50
	global_load_dword v56, v[4:5], off nt
	v_lshl_add_u64 v[4:5], s[90:91], 2, v[2:3]
	s_mul_i32 s90, s2, 52
	global_load_dword v57, v[4:5], off nt
	v_lshl_add_u64 v[4:5], s[90:91], 2, v[2:3]
	s_mul_i32 s90, s2, 54
	global_load_dword v58, v[4:5], off nt
	v_lshl_add_u64 v[4:5], s[90:91], 2, v[2:3]
	s_mul_i32 s90, s2, 56
	global_load_dword v59, v[4:5], off nt
	v_lshl_add_u64 v[4:5], s[90:91], 2, v[2:3]
	s_mul_i32 s90, s2, 58
	global_load_dword v60, v[4:5], off nt
	v_lshl_add_u64 v[4:5], s[90:91], 2, v[2:3]
	s_mul_i32 s90, s2, 60
	global_load_dword v61, v[4:5], off nt
	v_lshl_add_u64 v[4:5], s[90:91], 2, v[2:3]
	s_mul_i32 s90, s2, 62
	v_lshl_add_u64 v[2:3], s[90:91], 2, v[2:3]
	global_load_dword v62, v[4:5], off nt
	global_load_dword v63, v[2:3], off nt
	s_lshl_b32 s2, s26, 3
	s_add_i32 s22, s5, s2
	s_cmp_gt_i32 s22, 0xbbff
	s_cbranch_scc0 .LBB0_433

; __device__ __forceinline__ void t_load(float (&v)[32], const float* W, int K, int N, int item, int lane) {
;     const int nkb = K / 64, grp = item >> 3, w8 = item & 7, kb = 2 * (grp % (nkb / 2)) + (w8 & 1), nb = 4 * (grp / (nkb / 2)) + (w8 >> 1);
;     const float* p = W + (size_t)(64 * kb + (lane >> 5)) * N + 32 * nb + (lane & 31);
; #pragma unroll
;     for (int i = 0; i < 32; ++i) v[i] = p[(size_t)(2 * i) * N];
; __global__ void __launch_bounds__(NTHR, 2) mega_fwd(Args args) {
;     ...
;                     if (it + hstep < i1) { P0_DECODE(it + hstep, bW, bK, bN, bWT, bmode, br); t_load(B, bW, bK, bN, br, lane); }
.LBB0_469:
	s_lshr_b32 s22, s36, 7
	v_cvt_f32_u32_e32 v1, s22
	s_sub_i32 s24, 0, s22
	s_ashr_i32 s19, s37, 3
	s_abs_i32 s23, s19
	v_rcp_iflag_f32_e32 v1, v1
	s_ashr_i32 s18, s37, 31
	v_lshlrev_b32_e32 v4, 2, v96
	v_mov_b32_e32 v5, v0
	v_mul_f32_e32 v1, 0x4f7ffffe, v1
	v_cvt_u32_f32_e32 v1, v1
	s_nop 0
	v_readfirstlane_b32 s25, v1
	s_mul_i32 s24, s24, s25
	s_mul_hi_u32 s24, s25, s24
	s_add_i32 s25, s25, s24
	s_mul_hi_u32 s24, s23, s25
	s_mul_i32 s25, s24, s22
	s_sub_i32 s23, s23, s25
	s_add_i32 s25, s24, 1
	s_sub_i32 s27, s23, s22
	s_cmp_ge_u32 s23, s22
	s_cselect_b32 s24, s25, s24
	s_cselect_b32 s23, s27, s23
	s_add_i32 s25, s24, 1
	s_cmp_ge_u32 s23, s22
	s_cselect_b32 s23, s25, s24
	s_xor_b32 s23, s23, s18
	s_sub_i32 s18, s23, s18
	s_mul_i32 s22, s18, s22
	s_sub_i32 s19, s19, s22
	s_lshl_b32 s22, s37, 6
	s_lshl_b32 s19, s19, 7
	s_and_b32 s22, s22, 64
	s_or_b32 s22, s19, s22
	v_lshrrev_b32_e32 v1, 5, v97
	v_or_b32_e32 v1, s22, v1
	s_ashr_i32 s19, s19, 31
	s_mul_i32 s19, s19, s21
	v_mad_u64_u32 v[2:3], s[22:23], v1, s21, 0
	v_add_u32_e32 v3, s19, v3
	s_waitcnt lgkmcnt(0)
	v_lshl_add_u64 v[2:3], v[2:3], 2, s[16:17]
	s_lshl_b32 s17, s37, 4
	s_lshl_b32 s16, s18, 7
	s_and_b32 s17, s17, 0x60
	s_or_b32 s16, s16, s17
	s_ashr_i32 s17, s16, 31
	v_lshl_add_u64 v[2:3], s[16:17], 2, v[2:3]
	v_lshl_add_u64 v[2:3], v[2:3], 0, v[4:5]
	s_lshl_b32 s90, s21, 1
	v_lshl_add_u64 v[4:5], s[90:91], 2, v[2:3]
	s_lshl_b32 s90, s21, 2
	global_load_dword v64, v[2:3], off nt
	global_load_dword v65, v[4:5], off nt
	v_lshl_add_u64 v[4:5], s[90:91], 2, v[2:3]
	s_mul_i32 s90, s21, 6
	global_load_dword v66, v[4:5], off nt
	v_lshl_add_u64 v[4:5], s[90:91], 2, v[2:3]
	s_lshl_b32 s90, s21, 3
	global_load_dword v67, v[4:5], off nt
	v_lshl_add_u64 v[4:5], s[90:91], 2, v[2:3]
	s_mul_i32 s90, s21, 10
	global_load_dword v68, v[4:5], off nt
	v_lshl_add_u64 v[4:5], s[90:91], 2, v[2:3]
	s_mul_i32 s90, s21, 12
	global_load_dword v69, v[4:5], off nt
	v_lshl_add_u64 v[4:5], s[90:91], 2, v[2:3]
	s_mul_i32 s90, s21, 14
	global_load_dword v70, v[4:5], off nt
	v_lshl_add_u64 v[4:5], s[90:91], 2, v[2:3]
	s_lshl_b32 s90, s21, 4
	global_load_dword v71, v[4:5], off nt
	v_lshl_add_u64 v[4:5], s[90:91], 2, v[2:3]
	s_mul_i32 s90, s21, 18
	global_load_dword v72, v[4:5], off nt
	v_lshl_add_u64 v[4:5], s[90:91], 2, v[2:3]
	s_mul_i32 s90, s21, 20
	global_load_dword v73, v[4:5], off nt
	v_lshl_add_u64 v[4:5], s[90:91], 2, v[2:3]
	s_mul_i32 s90, s21, 22
	global_load_dword v74, v[4:5], off nt
	v_lshl_add_u64 v[4:5], s[90:91], 2, v[2:3]
	s_mul_i32 s90, s21, 24
	global_load_dword v75, v[4:5], off nt
	v_lshl_add_u64 v[4:5], s[90:91], 2, v[2:3]
	s_mul_i32 s90, s21, 26
	global_load_dword v76, v[4:5], off nt
	v_lshl_add_u64 v[4:5], s[90:91], 2, v[2:3]
	s_mul_i32 s90, s21, 28
	global_load_dword v77, v[4:5], off nt
	v_lshl_add_u64 v[4:5], s[90:91], 2, v[2:3]
	s_mul_i32 s90, s21, 30
	global_load_dword v78, v[4:5], off nt
	v_lshl_add_u64 v[4:5], s[90:91], 2, v[2:3]
	s_lshl_b32 s90, s21, 5
	global_load_dword v79, v[4:5], off nt
	v_lshl_add_u64 v[4:5], s[90:91], 2, v[2:3]
	s_mul_i32 s90, s21, 34
	global_load_dword v80, v[4:5], off nt
	v_lshl_add_u64 v[4:5], s[90:91], 2, v[2:3]
	s_mul_i32 s90, s21, 36
	global_load_dword v81, v[4:5], off nt
	v_lshl_add_u64 v[4:5], s[90:91], 2, v[2:3]
	s_mul_i32 s90, s21, 38
	global_load_dword v82, v[4:5], off nt
	v_lshl_add_u64 v[4:5], s[90:91], 2, v[2:3]
	s_mul_i32 s90, s21, 40
	global_load_dword v83, v[4:5], off nt
	v_lshl_add_u64 v[4:5], s[90:91], 2, v[2:3]
	s_mul_i32 s90, s21, 42
	global_load_dword v84, v[4:5], off nt
	v_lshl_add_u64 v[4:5], s[90:91], 2, v[2:3]
	s_mul_i32 s90, s21, 44
	global_load_dword v85, v[4:5], off nt
	v_lshl_add_u64 v[4:5], s[90:91], 2, v[2:3]
	s_mul_i32 s90, s21, 46
	global_load_dword v86, v[4:5], off nt
	v_lshl_add_u64 v[4:5], s[90:91], 2, v[2:3]
	s_mul_i32 s90, s21, 48
	global_load_dword v87, v[4:5], off nt
	v_lshl_add_u64 v[4:5], s[90:91], 2, v[2:3]
	s_mul_i32 s90, s21, 50
	global_load_dword v88, v[4:5], off nt
	v_lshl_add_u64 v[4:5], s[90:91], 2, v[2:3]
	s_mul_i32 s90, s21, 52
	global_load_dword v89, v[4:5], off nt
	v_lshl_add_u64 v[4:5], s[90:91], 2, v[2:3]
	s_mul_i32 s90, s21, 54
	global_load_dword v90, v[4:5], off nt
	v_lshl_add_u64 v[4:5], s[90:91], 2, v[2:3]
	s_mul_i32 s90, s21, 56
	global_load_dword v91, v[4:5], off nt
	v_lshl_add_u64 v[4:5], s[90:91], 2, v[2:3]
	s_mul_i32 s90, s21, 58
	global_load_dword v92, v[4:5], off nt
	v_lshl_add_u64 v[4:5], s[90:91], 2, v[2:3]
	s_mul_i32 s90, s21, 60
	global_load_dword v93, v[4:5], off nt
	v_lshl_add_u64 v[4:5], s[90:91], 2, v[2:3]
	s_mul_i32 s90, s21, 62
	v_lshl_add_u64 v[2:3], s[90:91], 2, v[2:3]
	global_load_dword v94, v[4:5], off nt
	global_load_dword v95, v[2:3], off nt
	v_readlane_b32 s24, v254, 46
	v_readlane_b32 s25, v254, 47
	s_andn2_b64 vcc, exec, s[14:15]
	s_cbranch_vccnz .LBB0_551

; __device__ __forceinline__ void t_load(float (&v)[32], const float* W, int K, int N, int item, int lane) {
;     const int nkb = K / 64, grp = item >> 3, w8 = item & 7, kb = 2 * (grp % (nkb / 2)) + (w8 & 1), nb = 4 * (grp / (nkb / 2)) + (w8 >> 1);
;     const float* p = W + (size_t)(64 * kb + (lane >> 5)) * N + 32 * nb + (lane & 31);
; #pragma unroll
;     for (int i = 0; i < 32; ++i) v[i] = p[(size_t)(2 * i) * N];
; __global__ void __launch_bounds__(NTHR, 2) mega_fwd(Args args) {
;     ...
;                           if (it + 2 * hstep < i1) { P0_DECODE(it + 2 * hstep, aW, aK, aN, aWT, amode, ar); t_load(A, aW, aK, aN, ar, lane); }
;                           __builtin_amdgcn_sched_barrier(0);
;                           t_emit(eK, eN, eWT, emode, scr, er, lane); }
;                         if (it + hstep < i1) { t_lds_write(B, scr, lane);
;                           const int eK = bK, eN = bN, emode = bmode, er = br; bf16* eWT = bWT;
;                           if (it + 3 * hstep < i1) { P0_DECODE(it + 3 * hstep, bW, bK, bN, bWT, bmode, br); t_load(B, bW, bK, bN, br, lane); }
.LBB0_471:
	s_lshr_b32 s35, s38, 7
	v_cvt_f32_u32_e32 v3, s35
	s_sub_i32 s54, 0, s35
	s_ashr_i32 s34, s5, 3
	s_abs_i32 s52, s34
	v_rcp_iflag_f32_e32 v3, v3
	s_ashr_i32 s51, s5, 31
	v_lshlrev_b32_e32 v12, 2, v96
	v_mov_b32_e32 v13, v0
	v_mul_f32_e32 v3, 0x4f7ffffe, v3
	v_cvt_u32_f32_e32 v3, v3
	s_nop 0
	v_readfirstlane_b32 s55, v3
	s_mul_i32 s54, s54, s55
	s_mul_hi_u32 s54, s55, s54
	s_add_i32 s55, s55, s54
	s_mul_hi_u32 s54, s52, s55
	s_mul_i32 s55, s54, s35
	s_sub_i32 s52, s52, s55
	s_add_i32 s55, s54, 1
	s_sub_i32 s57, s52, s35
	s_cmp_ge_u32 s52, s35
	s_cselect_b32 s54, s55, s54
	s_cselect_b32 s52, s57, s52
	s_add_i32 s55, s54, 1
	s_cmp_ge_u32 s52, s35
	s_cselect_b32 s52, s55, s54
	s_xor_b32 s52, s52, s51
	s_sub_i32 s51, s52, s51
	s_mul_i32 s35, s51, s35
	s_sub_i32 s34, s34, s35
	s_lshl_b32 s35, s5, 6
	s_lshl_b32 s34, s34, 7
	s_and_b32 s35, s35, 64
	s_or_b32 s35, s34, s35
	v_or_b32_e32 v3, s35, v1
	s_ashr_i32 s34, s34, 31
	s_mul_i32 s52, s34, s43
	v_mad_u64_u32 v[4:5], s[34:35], v3, s43, 0
	v_add_u32_e32 v5, s52, v5
	s_waitcnt lgkmcnt(0)
	v_lshl_add_u64 v[4:5], v[4:5], 2, s[30:31]
	s_lshl_b32 s31, s5, 4
	s_lshl_b32 s30, s51, 7
	s_and_b32 s31, s31, 0x60
	s_or_b32 s30, s30, s31
	s_ashr_i32 s31, s30, 31
	v_lshl_add_u64 v[4:5], s[30:31], 2, v[4:5]
	v_lshl_add_u64 v[4:5], v[4:5], 0, v[12:13]
	s_lshl_b32 s90, s43, 1
	v_lshl_add_u64 v[12:13], s[90:91], 2, v[4:5]
	s_lshl_b32 s90, s43, 2
	global_load_dword v64, v[4:5], off nt
	global_load_dword v65, v[12:13], off nt
	v_lshl_add_u64 v[12:13], s[90:91], 2, v[4:5]
	s_mul_i32 s90, s43, 6
	global_load_dword v66, v[12:13], off nt
	v_lshl_add_u64 v[12:13], s[90:91], 2, v[4:5]
	s_lshl_b32 s90, s43, 3
	global_load_dword v67, v[12:13], off nt
	v_lshl_add_u64 v[12:13], s[90:91], 2, v[4:5]
	s_mul_i32 s90, s43, 10
	global_load_dword v68, v[12:13], off nt
	v_lshl_add_u64 v[12:13], s[90:91], 2, v[4:5]
	s_mul_i32 s90, s43, 12
	global_load_dword v69, v[12:13], off nt
	v_lshl_add_u64 v[12:13], s[90:91], 2, v[4:5]
	s_mul_i32 s90, s43, 14
	global_load_dword v70, v[12:13], off nt
	v_lshl_add_u64 v[12:13], s[90:91], 2, v[4:5]
	s_lshl_b32 s90, s43, 4
	global_load_dword v71, v[12:13], off nt
	v_lshl_add_u64 v[12:13], s[90:91], 2, v[4:5]
	s_mul_i32 s90, s43, 18
	global_load_dword v72, v[12:13], off nt
	v_lshl_add_u64 v[12:13], s[90:91], 2, v[4:5]
	s_mul_i32 s90, s43, 20
	global_load_dword v73, v[12:13], off nt
	v_lshl_add_u64 v[12:13], s[90:91], 2, v[4:5]
	s_mul_i32 s90, s43, 22
	global_load_dword v74, v[12:13], off nt
	v_lshl_add_u64 v[12:13], s[90:91], 2, v[4:5]
	s_mul_i32 s90, s43, 24
	global_load_dword v75, v[12:13], off nt
	v_lshl_add_u64 v[12:13], s[90:91], 2, v[4:5]
	s_mul_i32 s90, s43, 26
	global_load_dword v76, v[12:13], off nt
	v_lshl_add_u64 v[12:13], s[90:91], 2, v[4:5]
	s_mul_i32 s90, s43, 28
	global_load_dword v77, v[12:13], off nt
	v_lshl_add_u64 v[12:13], s[90:91], 2, v[4:5]
	s_mul_i32 s90, s43, 30
	global_load_dword v78, v[12:13], off nt
	v_lshl_add_u64 v[12:13], s[90:91], 2, v[4:5]
	s_lshl_b32 s90, s43, 5
	global_load_dword v79, v[12:13], off nt
	v_lshl_add_u64 v[12:13], s[90:91], 2, v[4:5]
	s_mul_i32 s90, s43, 34
	global_load_dword v80, v[12:13], off nt
	v_lshl_add_u64 v[12:13], s[90:91], 2, v[4:5]
	s_mul_i32 s90, s43, 36
	global_load_dword v81, v[12:13], off nt
	v_lshl_add_u64 v[12:13], s[90:91], 2, v[4:5]
	s_mul_i32 s90, s43, 38
	global_load_dword v82, v[12:13], off nt
	v_lshl_add_u64 v[12:13], s[90:91], 2, v[4:5]
	s_mul_i32 s90, s43, 40
	global_load_dword v83, v[12:13], off nt
	v_lshl_add_u64 v[12:13], s[90:91], 2, v[4:5]
	s_mul_i32 s90, s43, 42
	global_load_dword v84, v[12:13], off nt
	v_lshl_add_u64 v[12:13], s[90:91], 2, v[4:5]
	s_mul_i32 s90, s43, 44
	global_load_dword v85, v[12:13], off nt
	v_lshl_add_u64 v[12:13], s[90:91], 2, v[4:5]
	s_mul_i32 s90, s43, 46
	global_load_dword v86, v[12:13], off nt
	v_lshl_add_u64 v[12:13], s[90:91], 2, v[4:5]
	s_mul_i32 s90, s43, 48
	global_load_dword v87, v[12:13], off nt
	v_lshl_add_u64 v[12:13], s[90:91], 2, v[4:5]
	s_mul_i32 s90, s43, 50
	global_load_dword v88, v[12:13], off nt
	v_lshl_add_u64 v[12:13], s[90:91], 2, v[4:5]
	s_mul_i32 s90, s43, 52
	global_load_dword v89, v[12:13], off nt
	v_lshl_add_u64 v[12:13], s[90:91], 2, v[4:5]
	s_mul_i32 s90, s43, 54
	global_load_dword v90, v[12:13], off nt
	v_lshl_add_u64 v[12:13], s[90:91], 2, v[4:5]
	s_mul_i32 s90, s43, 56
	global_load_dword v91, v[12:13], off nt
	v_lshl_add_u64 v[12:13], s[90:91], 2, v[4:5]
	s_mul_i32 s90, s43, 58
	global_load_dword v92, v[12:13], off nt
	v_lshl_add_u64 v[12:13], s[90:91], 2, v[4:5]
	s_mul_i32 s90, s43, 60
	global_load_dword v93, v[12:13], off nt
	v_lshl_add_u64 v[12:13], s[90:91], 2, v[4:5]
	s_mul_i32 s90, s43, 62
	v_lshl_add_u64 v[4:5], s[90:91], 2, v[4:5]
	global_load_dword v94, v[12:13], off nt
	global_load_dword v95, v[4:5], off nt

; __device__ __forceinline__ void t_load(float (&v)[32], const float* W, int K, int N, int item, int lane) {
;     const int nkb = K / 64, grp = item >> 3, w8 = item & 7, kb = 2 * (grp % (nkb / 2)) + (w8 & 1), nb = 4 * (grp / (nkb / 2)) + (w8 >> 1);
;     const float* p = W + (size_t)(64 * kb + (lane >> 5)) * N + 32 * nb + (lane & 31);
; #pragma unroll
;     for (int i = 0; i < 32; ++i) v[i] = p[(size_t)(2 * i) * N];
; __global__ void __launch_bounds__(NTHR, 2) mega_fwd(Args args) {
;     ...
;                           if (it + 2 * hstep < i1) { P0_DECODE(it + 2 * hstep, aW, aK, aN, aWT, amode, ar); t_load(A, aW, aK, aN, ar, lane); }
;                           __builtin_amdgcn_sched_barrier(0);
;                           t_emit(eK, eN, eWT, emode, scr, er, lane); }
;                         if (it + hstep < i1) { t_lds_write(B, scr, lane);
;                           const int eK = bK, eN = bN, emode = bmode, er = br; bf16* eWT = bWT;
;                           if (it + 3 * hstep < i1) { P0_DECODE(it + 3 * hstep, bW, bK, bN, bWT, bmode, br); t_load(B, bW, bK, bN, br, lane); }
.LBB0_511:
	s_lshr_b32 s35, s46, 7
	v_cvt_f32_u32_e32 v3, s35
	s_sub_i32 s55, 0, s35
	s_ashr_i32 s34, s45, 3
	s_abs_i32 s54, s34
	v_rcp_iflag_f32_e32 v3, v3
	s_ashr_i32 s52, s45, 31
	v_lshlrev_b32_e32 v20, 2, v96
	v_mov_b32_e32 v21, v0
	v_mul_f32_e32 v3, 0x4f7ffffe, v3
	v_cvt_u32_f32_e32 v3, v3
	s_nop 0
	v_readfirstlane_b32 s57, v3
	s_mul_i32 s55, s55, s57
	s_mul_hi_u32 s55, s57, s55
	s_add_i32 s57, s57, s55
	s_mul_hi_u32 s55, s54, s57
	s_mul_i32 s57, s55, s35
	s_sub_i32 s54, s54, s57
	s_add_i32 s57, s55, 1
	s_sub_i32 s58, s54, s35
	s_cmp_ge_u32 s54, s35
	s_cselect_b32 s55, s57, s55
	s_cselect_b32 s54, s58, s54
	s_add_i32 s57, s55, 1
	s_cmp_ge_u32 s54, s35
	s_cselect_b32 s54, s57, s55
	s_xor_b32 s54, s54, s52
	s_sub_i32 s52, s54, s52
	s_mul_i32 s35, s52, s35
	s_sub_i32 s34, s34, s35
	s_lshl_b32 s35, s45, 6
	s_lshl_b32 s34, s34, 7
	s_and_b32 s35, s35, 64
	s_or_b32 s35, s34, s35
	v_or_b32_e32 v3, s35, v1
	s_ashr_i32 s34, s34, 31
	s_mul_i32 s54, s34, s51
	v_mad_u64_u32 v[4:5], s[34:35], v3, s51, 0
	v_add_u32_e32 v5, s54, v5
	s_waitcnt lgkmcnt(0)
	v_lshl_add_u64 v[4:5], v[4:5], 2, s[30:31]
	s_lshl_b32 s31, s45, 4
	s_lshl_b32 s30, s52, 7
	s_and_b32 s31, s31, 0x60
	s_or_b32 s30, s30, s31
	s_ashr_i32 s31, s30, 31
	v_lshl_add_u64 v[4:5], s[30:31], 2, v[4:5]
	v_lshl_add_u64 v[4:5], v[4:5], 0, v[20:21]
	s_lshl_b32 s90, s51, 1
	v_lshl_add_u64 v[20:21], s[90:91], 2, v[4:5]
	s_lshl_b32 s90, s51, 2
	global_load_dword v32, v[4:5], off nt
	global_load_dword v33, v[20:21], off nt
	v_lshl_add_u64 v[20:21], s[90:91], 2, v[4:5]
	s_mul_i32 s90, s51, 6
	global_load_dword v34, v[20:21], off nt
	v_lshl_add_u64 v[20:21], s[90:91], 2, v[4:5]
	s_lshl_b32 s90, s51, 3
	global_load_dword v35, v[20:21], off nt
	v_lshl_add_u64 v[20:21], s[90:91], 2, v[4:5]
	s_mul_i32 s90, s51, 10
	global_load_dword v36, v[20:21], off nt
	v_lshl_add_u64 v[20:21], s[90:91], 2, v[4:5]
	s_mul_i32 s90, s51, 12
	global_load_dword v37, v[20:21], off nt
	v_lshl_add_u64 v[20:21], s[90:91], 2, v[4:5]
	s_mul_i32 s90, s51, 14
	global_load_dword v38, v[20:21], off nt
	v_lshl_add_u64 v[20:21], s[90:91], 2, v[4:5]
	s_lshl_b32 s90, s51, 4
	global_load_dword v39, v[20:21], off nt
	v_lshl_add_u64 v[20:21], s[90:91], 2, v[4:5]
	s_mul_i32 s90, s51, 18
	global_load_dword v40, v[20:21], off nt
	v_lshl_add_u64 v[20:21], s[90:91], 2, v[4:5]
	s_mul_i32 s90, s51, 20
	global_load_dword v41, v[20:21], off nt
	v_lshl_add_u64 v[20:21], s[90:91], 2, v[4:5]
	s_mul_i32 s90, s51, 22
	global_load_dword v42, v[20:21], off nt
	v_lshl_add_u64 v[20:21], s[90:91], 2, v[4:5]
	s_mul_i32 s90, s51, 24
	global_load_dword v43, v[20:21], off nt
	v_lshl_add_u64 v[20:21], s[90:91], 2, v[4:5]
	s_mul_i32 s90, s51, 26
	global_load_dword v44, v[20:21], off nt
	v_lshl_add_u64 v[20:21], s[90:91], 2, v[4:5]
	s_mul_i32 s90, s51, 28
	global_load_dword v45, v[20:21], off nt
	v_lshl_add_u64 v[20:21], s[90:91], 2, v[4:5]
	s_mul_i32 s90, s51, 30
	global_load_dword v46, v[20:21], off nt
	v_lshl_add_u64 v[20:21], s[90:91], 2, v[4:5]
	s_lshl_b32 s90, s51, 5
	global_load_dword v47, v[20:21], off nt
	v_lshl_add_u64 v[20:21], s[90:91], 2, v[4:5]
	s_mul_i32 s90, s51, 34
	global_load_dword v48, v[20:21], off nt
	v_lshl_add_u64 v[20:21], s[90:91], 2, v[4:5]
	s_mul_i32 s90, s51, 36
	global_load_dword v49, v[20:21], off nt
	v_lshl_add_u64 v[20:21], s[90:91], 2, v[4:5]
	s_mul_i32 s90, s51, 38
	global_load_dword v50, v[20:21], off nt
	v_lshl_add_u64 v[20:21], s[90:91], 2, v[4:5]
	s_mul_i32 s90, s51, 40
	global_load_dword v51, v[20:21], off nt
	v_lshl_add_u64 v[20:21], s[90:91], 2, v[4:5]
	s_mul_i32 s90, s51, 42
	global_load_dword v52, v[20:21], off nt
	v_lshl_add_u64 v[20:21], s[90:91], 2, v[4:5]
	s_mul_i32 s90, s51, 44
	global_load_dword v53, v[20:21], off nt
	v_lshl_add_u64 v[20:21], s[90:91], 2, v[4:5]
	s_mul_i32 s90, s51, 46
	global_load_dword v54, v[20:21], off nt
	v_lshl_add_u64 v[20:21], s[90:91], 2, v[4:5]
	s_mul_i32 s90, s51, 48
	global_load_dword v55, v[20:21], off nt
	v_lshl_add_u64 v[20:21], s[90:91], 2, v[4:5]
	s_mul_i32 s90, s51, 50
	global_load_dword v56, v[20:21], off nt
	v_lshl_add_u64 v[20:21], s[90:91], 2, v[4:5]
	s_mul_i32 s90, s51, 52
	global_load_dword v57, v[20:21], off nt
	v_lshl_add_u64 v[20:21], s[90:91], 2, v[4:5]
	s_mul_i32 s90, s51, 54
	global_load_dword v58, v[20:21], off nt
	v_lshl_add_u64 v[20:21], s[90:91], 2, v[4:5]
	s_mul_i32 s90, s51, 56
	global_load_dword v59, v[20:21], off nt
	v_lshl_add_u64 v[20:21], s[90:91], 2, v[4:5]
	s_mul_i32 s90, s51, 58
	global_load_dword v60, v[20:21], off nt
	v_lshl_add_u64 v[20:21], s[90:91], 2, v[4:5]
	s_mul_i32 s90, s51, 60
	global_load_dword v61, v[20:21], off nt
	v_lshl_add_u64 v[20:21], s[90:91], 2, v[4:5]
	s_mul_i32 s90, s51, 62
	v_lshl_add_u64 v[4:5], s[90:91], 2, v[4:5]
	global_load_dword v62, v[20:21], off nt
	global_load_dword v63, v[4:5], off nt
